# unrolled GEMM loops: first k-step MFMAs take the inline 0 as C (no accumulator zeroing moves)
# speedup vs baseline: 1.0190x; 1.0022x over previous
.LBB0_213:
	s_andn2_b64 vcc, exec, s[6:7]
	s_mov_b64 s[6:7], 0
	s_cbranch_vccnz .LBB0_209
	s_ashr_i32 s39, s38, 31
	s_lshl_b64 s[6:7], s[38:39], 18
	s_add_u32 s72, s3, s6
	s_addc_u32 s73, s33, s7
	s_ashr_i32 s11, s10, 31
	s_lshl_b64 s[34:35], s[10:11], 19
	s_add_u32 s74, s50, s34
	s_addc_u32 s75, s51, s35
	v_readfirstlane_b32 s11, v184
	s_nop 3
	s_lshr_b32 s0, s11, 6
	s_lshr_b32 s39, s11, 4
	s_and_b32 s39, s39, 4
	v_lshl_or_b32 v2, s0, 3, v210
	v_bitop3_b32 v8, s39, v208, v209 bitop3:0x36
	v_lshlrev_b32_e32 v2, 11, v2
	v_lshlrev_b32_e32 v8, 4, v8
	v_or_b32_e32 v144, v2, v8
	v_add_u32_e32 v145, 0x20000, v144
	v_add_u32_e32 v146, 0x40000, v144
	v_add_u32_e32 v147, 0x60000, v144
	s_lshl_b32 s79, s0, 10
	s_lshr_b32 s9, s11, 1
	s_and_b32 s9, s9, 0x1ffffc0
	v_and_or_b32 v4, s11, 64, v189
	v_lshlrev_b32_e32 v106, 7, v4
	v_or_b32_e32 v4, s9, v189
	v_lshlrev_b32_e32 v107, 7, v4
	s_add_i32 m0, s79, 0x100
	s_nop 0
	global_load_lds_dwordx4 v144, s[72:73]
	s_add_i32 m0, s79, 0x2100
	s_nop 0
	global_load_lds_dwordx4 v145, s[72:73]
	s_add_i32 m0, s79, 0x4100
	s_nop 0
	global_load_lds_dwordx4 v144, s[74:75]
	s_add_i32 m0, s79, 0x6100
	s_nop 0
	global_load_lds_dwordx4 v145, s[74:75]
	s_add_i32 m0, s79, 0x8100
	s_nop 0
	global_load_lds_dwordx4 v146, s[74:75]
	s_add_i32 m0, s79, 0xa100
	s_nop 0
	global_load_lds_dwordx4 v147, s[74:75]
	s_add_u32 s72, s72, 0x80
	s_addc_u32 s73, s73, 0
	s_add_u32 s74, s74, 0x80
	s_addc_u32 s75, s75, 0
	s_add_i32 m0, s79, 0xc100
	s_nop 0
	global_load_lds_dwordx4 v144, s[72:73]
	s_add_i32 m0, s79, 0xe100
	s_nop 0
	global_load_lds_dwordx4 v145, s[72:73]
	s_add_i32 m0, s79, 0x10100
	s_nop 0
	global_load_lds_dwordx4 v144, s[74:75]
	s_add_i32 m0, s79, 0x12100
	s_nop 0
	global_load_lds_dwordx4 v145, s[74:75]
	s_add_i32 m0, s79, 0x14100
	s_nop 0
	global_load_lds_dwordx4 v146, s[74:75]
	s_add_i32 m0, s79, 0x16100
	s_nop 0
	global_load_lds_dwordx4 v147, s[74:75]
	s_add_u32 s72, s72, 0x80
	s_addc_u32 s73, s73, 0
	s_add_u32 s74, s74, 0x80
	s_addc_u32 s75, s75, 0
	s_movk_i32 s81, 0x100
	v_add3_u32 v216, s81, v106, v211
	v_add3_u32 v217, s81, v106, v212
	v_add3_u32 v218, s81, v106, v213
	v_add3_u32 v219, s81, v106, v214
	s_movk_i32 s81, 0x4100
	v_add3_u32 v220, s81, v107, v211
	v_add3_u32 v221, s81, v107, v212
	v_add3_u32 v222, s81, v107, v213
	v_add3_u32 v223, s81, v107, v214
	s_mov_b32 s81, 0x1b800
	v_add_u32_e32 v224, s81, v216
	v_add_u32_e32 v228, s81, v220
	v_add_u32_e32 v225, s81, v217
	v_add_u32_e32 v229, s81, v221
	v_add_u32_e32 v226, s81, v218
	v_add_u32_e32 v230, s81, v222
	v_add_u32_e32 v227, s81, v219
	v_add_u32_e32 v231, s81, v223
	s_waitcnt vmcnt(6)
	s_barrier
	ds_read_b128 v[108:111], v216
	ds_read_b128 v[116:119], v220
	ds_read_b128 v[120:123], v220 offset:4096
	ds_read_b128 v[112:115], v216 offset:4096
.Lg1_loop:
	ds_read_b128 v[126:129], v217
	ds_read_b128 v[134:137], v221
	ds_read_b128 v[138:141], v221 offset:4096
	ds_read_b128 v[130:133], v217 offset:4096
	s_setprio 1
	s_add_i32 m0, s79, 0x1b900
	s_waitcnt lgkmcnt(6)
	v_mfma_f32_32x32x16_bf16 v[50:65], v[108:111], v[116:119], 0
	global_load_lds_dwordx4 v144, s[72:73]
	s_add_i32 m0, s79, 0x1d900
	s_waitcnt lgkmcnt(5)
	v_mfma_f32_32x32x16_bf16 v[18:33], v[108:111], v[120:123], 0
	global_load_lds_dwordx4 v145, s[72:73]
	s_waitcnt lgkmcnt(4)
	v_mfma_f32_32x32x16_bf16 v[34:49], v[112:115], v[116:119], 0
	v_mfma_f32_32x32x16_bf16 v[2:17], v[112:115], v[120:123], 0
	s_setprio 0
	ds_read_b128 v[108:111], v218
	ds_read_b128 v[116:119], v222
	ds_read_b128 v[120:123], v222 offset:4096
	ds_read_b128 v[112:115], v218 offset:4096
	s_setprio 1
	s_add_i32 m0, s79, 0x1f900
	s_waitcnt lgkmcnt(6)
	v_mfma_f32_32x32x16_bf16 v[50:65], v[126:129], v[134:137], v[50:65]
	global_load_lds_dwordx4 v144, s[74:75]
	s_add_i32 m0, s79, 0x21900
	s_waitcnt lgkmcnt(5)
	v_mfma_f32_32x32x16_bf16 v[18:33], v[126:129], v[138:141], v[18:33]
	global_load_lds_dwordx4 v145, s[74:75]
	s_waitcnt lgkmcnt(4)
	v_mfma_f32_32x32x16_bf16 v[34:49], v[130:133], v[134:137], v[34:49]
	v_mfma_f32_32x32x16_bf16 v[2:17], v[130:133], v[138:141], v[2:17]
	s_setprio 0
	ds_read_b128 v[126:129], v219
	ds_read_b128 v[134:137], v223
	ds_read_b128 v[138:141], v223 offset:4096
	ds_read_b128 v[130:133], v219 offset:4096
	s_setprio 1
	s_add_i32 m0, s79, 0x23900
	s_waitcnt lgkmcnt(6)
	v_mfma_f32_32x32x16_bf16 v[50:65], v[108:111], v[116:119], v[50:65]
	global_load_lds_dwordx4 v146, s[74:75]
	s_add_i32 m0, s79, 0x25900
	s_waitcnt lgkmcnt(5)
	v_mfma_f32_32x32x16_bf16 v[18:33], v[108:111], v[120:123], v[18:33]
	global_load_lds_dwordx4 v147, s[74:75]
	s_waitcnt lgkmcnt(4)
	v_mfma_f32_32x32x16_bf16 v[34:49], v[112:115], v[116:119], v[34:49]
	v_mfma_f32_32x32x16_bf16 v[2:17], v[112:115], v[120:123], v[2:17]
	s_setprio 0
	s_add_u32 s72, s72, 0x80
	s_addc_u32 s73, s73, 0
	s_add_u32 s74, s74, 0x80
	s_addc_u32 s75, s75, 0
	s_waitcnt lgkmcnt(0)
	s_waitcnt vmcnt(6)
	s_barrier
	ds_read_b128 v[108:111], v216 offset:49152
	ds_read_b128 v[116:119], v220 offset:49152
	ds_read_b128 v[120:123], v220 offset:53248
	ds_read_b128 v[112:115], v216 offset:53248
	s_setprio 1
	v_mfma_f32_32x32x16_bf16 v[50:65], v[126:129], v[134:137], v[50:65]
	v_mfma_f32_32x32x16_bf16 v[18:33], v[126:129], v[138:141], v[18:33]
	v_mfma_f32_32x32x16_bf16 v[34:49], v[130:133], v[134:137], v[34:49]
	v_mfma_f32_32x32x16_bf16 v[2:17], v[130:133], v[138:141], v[2:17]
	s_setprio 0
	ds_read_b128 v[126:129], v217 offset:49152
	ds_read_b128 v[134:137], v221 offset:49152
	ds_read_b128 v[138:141], v221 offset:53248
	ds_read_b128 v[130:133], v217 offset:53248
	s_setprio 1
	s_add_i32 m0, s79, 0x100
	s_waitcnt lgkmcnt(6)
	v_mfma_f32_32x32x16_bf16 v[50:65], v[108:111], v[116:119], v[50:65]
	global_load_lds_dwordx4 v144, s[72:73]
	s_add_i32 m0, s79, 0x2100
	s_waitcnt lgkmcnt(5)
	v_mfma_f32_32x32x16_bf16 v[18:33], v[108:111], v[120:123], v[18:33]
	global_load_lds_dwordx4 v145, s[72:73]
	s_waitcnt lgkmcnt(4)
	v_mfma_f32_32x32x16_bf16 v[34:49], v[112:115], v[116:119], v[34:49]
	v_mfma_f32_32x32x16_bf16 v[2:17], v[112:115], v[120:123], v[2:17]
	s_setprio 0
	ds_read_b128 v[108:111], v218 offset:49152
	ds_read_b128 v[116:119], v222 offset:49152
	ds_read_b128 v[120:123], v222 offset:53248
	ds_read_b128 v[112:115], v218 offset:53248
	s_setprio 1
	s_add_i32 m0, s79, 0x4100
	s_waitcnt lgkmcnt(6)
	v_mfma_f32_32x32x16_bf16 v[50:65], v[126:129], v[134:137], v[50:65]
	global_load_lds_dwordx4 v144, s[74:75]
	s_add_i32 m0, s79, 0x6100
	s_waitcnt lgkmcnt(5)
	v_mfma_f32_32x32x16_bf16 v[18:33], v[126:129], v[138:141], v[18:33]
	global_load_lds_dwordx4 v145, s[74:75]
	s_waitcnt lgkmcnt(4)
	v_mfma_f32_32x32x16_bf16 v[34:49], v[130:133], v[134:137], v[34:49]
	v_mfma_f32_32x32x16_bf16 v[2:17], v[130:133], v[138:141], v[2:17]
	s_setprio 0
	ds_read_b128 v[126:129], v219 offset:49152
	ds_read_b128 v[134:137], v223 offset:49152
	ds_read_b128 v[138:141], v223 offset:53248
	ds_read_b128 v[130:133], v219 offset:53248
	s_setprio 1
	s_add_i32 m0, s79, 0x8100
	s_waitcnt lgkmcnt(6)
	v_mfma_f32_32x32x16_bf16 v[50:65], v[108:111], v[116:119], v[50:65]
	global_load_lds_dwordx4 v146, s[74:75]
	s_add_i32 m0, s79, 0xa100
	s_waitcnt lgkmcnt(5)
	v_mfma_f32_32x32x16_bf16 v[18:33], v[108:111], v[120:123], v[18:33]
	global_load_lds_dwordx4 v147, s[74:75]
	s_waitcnt lgkmcnt(4)
	v_mfma_f32_32x32x16_bf16 v[34:49], v[112:115], v[116:119], v[34:49]
	v_mfma_f32_32x32x16_bf16 v[2:17], v[112:115], v[120:123], v[2:17]
	s_setprio 0
	s_add_u32 s72, s72, 0x80
	s_addc_u32 s73, s73, 0
	s_add_u32 s74, s74, 0x80
	s_addc_u32 s75, s75, 0
	s_waitcnt lgkmcnt(0)
	s_waitcnt vmcnt(6)
	s_barrier
	ds_read_b128 v[108:111], v224
	ds_read_b128 v[116:119], v228
	ds_read_b128 v[120:123], v228 offset:4096
	ds_read_b128 v[112:115], v224 offset:4096
	s_setprio 1
	v_mfma_f32_32x32x16_bf16 v[50:65], v[126:129], v[134:137], v[50:65]
	v_mfma_f32_32x32x16_bf16 v[18:33], v[126:129], v[138:141], v[18:33]
	v_mfma_f32_32x32x16_bf16 v[34:49], v[130:133], v[134:137], v[34:49]
	v_mfma_f32_32x32x16_bf16 v[2:17], v[130:133], v[138:141], v[2:17]
	s_setprio 0
	ds_read_b128 v[126:129], v225
	ds_read_b128 v[134:137], v229
	ds_read_b128 v[138:141], v229 offset:4096
	ds_read_b128 v[130:133], v225 offset:4096
	s_setprio 1
	s_add_i32 m0, s79, 0xc100
	s_waitcnt lgkmcnt(6)
	v_mfma_f32_32x32x16_bf16 v[50:65], v[108:111], v[116:119], v[50:65]
	global_load_lds_dwordx4 v144, s[72:73]
	s_add_i32 m0, s79, 0xe100
	s_waitcnt lgkmcnt(5)
	v_mfma_f32_32x32x16_bf16 v[18:33], v[108:111], v[120:123], v[18:33]
	global_load_lds_dwordx4 v145, s[72:73]
	s_waitcnt lgkmcnt(4)
	v_mfma_f32_32x32x16_bf16 v[34:49], v[112:115], v[116:119], v[34:49]
	v_mfma_f32_32x32x16_bf16 v[2:17], v[112:115], v[120:123], v[2:17]
	s_setprio 0
	ds_read_b128 v[108:111], v226
	ds_read_b128 v[116:119], v230
	ds_read_b128 v[120:123], v230 offset:4096
	ds_read_b128 v[112:115], v226 offset:4096
	s_setprio 1
	s_add_i32 m0, s79, 0x10100
	s_waitcnt lgkmcnt(6)
	v_mfma_f32_32x32x16_bf16 v[50:65], v[126:129], v[134:137], v[50:65]
	global_load_lds_dwordx4 v144, s[74:75]
	s_add_i32 m0, s79, 0x12100
	s_waitcnt lgkmcnt(5)
	v_mfma_f32_32x32x16_bf16 v[18:33], v[126:129], v[138:141], v[18:33]
	global_load_lds_dwordx4 v145, s[74:75]
	s_waitcnt lgkmcnt(4)
	v_mfma_f32_32x32x16_bf16 v[34:49], v[130:133], v[134:137], v[34:49]
	v_mfma_f32_32x32x16_bf16 v[2:17], v[130:133], v[138:141], v[2:17]
	s_setprio 0
	ds_read_b128 v[126:129], v227
	ds_read_b128 v[134:137], v231
	ds_read_b128 v[138:141], v231 offset:4096
	ds_read_b128 v[130:133], v227 offset:4096
	s_setprio 1
	s_add_i32 m0, s79, 0x14100
	s_waitcnt lgkmcnt(6)
	v_mfma_f32_32x32x16_bf16 v[50:65], v[108:111], v[116:119], v[50:65]
	global_load_lds_dwordx4 v146, s[74:75]
	s_add_i32 m0, s79, 0x16100
	s_waitcnt lgkmcnt(5)
	v_mfma_f32_32x32x16_bf16 v[18:33], v[108:111], v[120:123], v[18:33]
	global_load_lds_dwordx4 v147, s[74:75]
	s_waitcnt lgkmcnt(4)
	v_mfma_f32_32x32x16_bf16 v[34:49], v[112:115], v[116:119], v[34:49]
	v_mfma_f32_32x32x16_bf16 v[2:17], v[112:115], v[120:123], v[2:17]
	s_setprio 0
	s_add_u32 s72, s72, 0x80
	s_addc_u32 s73, s73, 0
	s_add_u32 s74, s74, 0x80
	s_addc_u32 s75, s75, 0
	s_waitcnt lgkmcnt(0)
	s_waitcnt vmcnt(6)
	s_barrier
	ds_read_b128 v[108:111], v216
	ds_read_b128 v[116:119], v220
	ds_read_b128 v[120:123], v220 offset:4096
	ds_read_b128 v[112:115], v216 offset:4096
	s_setprio 1
	v_mfma_f32_32x32x16_bf16 v[50:65], v[126:129], v[134:137], v[50:65]
	v_mfma_f32_32x32x16_bf16 v[18:33], v[126:129], v[138:141], v[18:33]
	v_mfma_f32_32x32x16_bf16 v[34:49], v[130:133], v[134:137], v[34:49]
	v_mfma_f32_32x32x16_bf16 v[2:17], v[130:133], v[138:141], v[2:17]
	s_setprio 0
	ds_read_b128 v[126:129], v217
	ds_read_b128 v[134:137], v221
	ds_read_b128 v[138:141], v221 offset:4096
	ds_read_b128 v[130:133], v217 offset:4096
	s_setprio 1
	s_add_i32 m0, s79, 0x1b900
	s_waitcnt lgkmcnt(6)
	v_mfma_f32_32x32x16_bf16 v[50:65], v[108:111], v[116:119], v[50:65]
	global_load_lds_dwordx4 v144, s[72:73]
	s_add_i32 m0, s79, 0x1d900
	s_waitcnt lgkmcnt(5)
	v_mfma_f32_32x32x16_bf16 v[18:33], v[108:111], v[120:123], v[18:33]
	global_load_lds_dwordx4 v145, s[72:73]
	s_waitcnt lgkmcnt(4)
	v_mfma_f32_32x32x16_bf16 v[34:49], v[112:115], v[116:119], v[34:49]
	v_mfma_f32_32x32x16_bf16 v[2:17], v[112:115], v[120:123], v[2:17]
	s_setprio 0
	ds_read_b128 v[108:111], v218
	ds_read_b128 v[116:119], v222
	ds_read_b128 v[120:123], v222 offset:4096
	ds_read_b128 v[112:115], v218 offset:4096
	s_setprio 1
	s_add_i32 m0, s79, 0x1f900
	s_waitcnt lgkmcnt(6)
	v_mfma_f32_32x32x16_bf16 v[50:65], v[126:129], v[134:137], v[50:65]
	global_load_lds_dwordx4 v144, s[74:75]
	s_add_i32 m0, s79, 0x21900
	s_waitcnt lgkmcnt(5)
	v_mfma_f32_32x32x16_bf16 v[18:33], v[126:129], v[138:141], v[18:33]
	global_load_lds_dwordx4 v145, s[74:75]
	s_waitcnt lgkmcnt(4)
	v_mfma_f32_32x32x16_bf16 v[34:49], v[130:133], v[134:137], v[34:49]
	v_mfma_f32_32x32x16_bf16 v[2:17], v[130:133], v[138:141], v[2:17]
	s_setprio 0
	ds_read_b128 v[126:129], v219
	ds_read_b128 v[134:137], v223
	ds_read_b128 v[138:141], v223 offset:4096
	ds_read_b128 v[130:133], v219 offset:4096
	s_setprio 1
	s_add_i32 m0, s79, 0x23900
	s_waitcnt lgkmcnt(6)
	v_mfma_f32_32x32x16_bf16 v[50:65], v[108:111], v[116:119], v[50:65]
	global_load_lds_dwordx4 v146, s[74:75]
	s_add_i32 m0, s79, 0x25900
	s_waitcnt lgkmcnt(5)
	v_mfma_f32_32x32x16_bf16 v[18:33], v[108:111], v[120:123], v[18:33]
	global_load_lds_dwordx4 v147, s[74:75]
	s_waitcnt lgkmcnt(4)
	v_mfma_f32_32x32x16_bf16 v[34:49], v[112:115], v[116:119], v[34:49]
	v_mfma_f32_32x32x16_bf16 v[2:17], v[112:115], v[120:123], v[2:17]
	s_setprio 0
	s_add_u32 s72, s72, 0x80
	s_addc_u32 s73, s73, 0
	s_add_u32 s74, s74, 0x80
	s_addc_u32 s75, s75, 0
	s_waitcnt lgkmcnt(0)
	s_waitcnt vmcnt(6)
	s_barrier
	ds_read_b128 v[108:111], v216 offset:49152
	ds_read_b128 v[116:119], v220 offset:49152
	ds_read_b128 v[120:123], v220 offset:53248
	ds_read_b128 v[112:115], v216 offset:53248
	s_setprio 1
	v_mfma_f32_32x32x16_bf16 v[50:65], v[126:129], v[134:137], v[50:65]
	v_mfma_f32_32x32x16_bf16 v[18:33], v[126:129], v[138:141], v[18:33]
	v_mfma_f32_32x32x16_bf16 v[34:49], v[130:133], v[134:137], v[34:49]
	v_mfma_f32_32x32x16_bf16 v[2:17], v[130:133], v[138:141], v[2:17]
	s_setprio 0
	ds_read_b128 v[126:129], v217 offset:49152
	ds_read_b128 v[134:137], v221 offset:49152
	ds_read_b128 v[138:141], v221 offset:53248
	ds_read_b128 v[130:133], v217 offset:53248
	s_setprio 1
	s_add_i32 m0, s79, 0x100
	s_waitcnt lgkmcnt(6)
	v_mfma_f32_32x32x16_bf16 v[50:65], v[108:111], v[116:119], v[50:65]
	global_load_lds_dwordx4 v144, s[72:73]
	s_add_i32 m0, s79, 0x2100
	s_waitcnt lgkmcnt(5)
	v_mfma_f32_32x32x16_bf16 v[18:33], v[108:111], v[120:123], v[18:33]
	global_load_lds_dwordx4 v145, s[72:73]
	s_waitcnt lgkmcnt(4)
	v_mfma_f32_32x32x16_bf16 v[34:49], v[112:115], v[116:119], v[34:49]
	v_mfma_f32_32x32x16_bf16 v[2:17], v[112:115], v[120:123], v[2:17]
	s_setprio 0
	ds_read_b128 v[108:111], v218 offset:49152
	ds_read_b128 v[116:119], v222 offset:49152
	ds_read_b128 v[120:123], v222 offset:53248
	ds_read_b128 v[112:115], v218 offset:53248
	s_setprio 1
	s_add_i32 m0, s79, 0x4100
	s_waitcnt lgkmcnt(6)
	v_mfma_f32_32x32x16_bf16 v[50:65], v[126:129], v[134:137], v[50:65]
	global_load_lds_dwordx4 v144, s[74:75]
	s_add_i32 m0, s79, 0x6100
	s_waitcnt lgkmcnt(5)
	v_mfma_f32_32x32x16_bf16 v[18:33], v[126:129], v[138:141], v[18:33]
	global_load_lds_dwordx4 v145, s[74:75]
	s_waitcnt lgkmcnt(4)
	v_mfma_f32_32x32x16_bf16 v[34:49], v[130:133], v[134:137], v[34:49]
	v_mfma_f32_32x32x16_bf16 v[2:17], v[130:133], v[138:141], v[2:17]
	s_setprio 0
	ds_read_b128 v[126:129], v219 offset:49152
	ds_read_b128 v[134:137], v223 offset:49152
	ds_read_b128 v[138:141], v223 offset:53248
	ds_read_b128 v[130:133], v219 offset:53248
	s_setprio 1
	s_add_i32 m0, s79, 0x8100
	s_waitcnt lgkmcnt(6)
	v_mfma_f32_32x32x16_bf16 v[50:65], v[108:111], v[116:119], v[50:65]
	global_load_lds_dwordx4 v146, s[74:75]
	s_add_i32 m0, s79, 0xa100
	s_waitcnt lgkmcnt(5)
	v_mfma_f32_32x32x16_bf16 v[18:33], v[108:111], v[120:123], v[18:33]
	global_load_lds_dwordx4 v147, s[74:75]
	s_waitcnt lgkmcnt(4)
	v_mfma_f32_32x32x16_bf16 v[34:49], v[112:115], v[116:119], v[34:49]
	v_mfma_f32_32x32x16_bf16 v[2:17], v[112:115], v[120:123], v[2:17]
	s_setprio 0
	s_add_u32 s72, s72, 0x80
	s_addc_u32 s73, s73, 0
	s_add_u32 s74, s74, 0x80
	s_addc_u32 s75, s75, 0
	s_waitcnt lgkmcnt(0)
	s_waitcnt vmcnt(6)
	s_barrier
	ds_read_b128 v[108:111], v224
	ds_read_b128 v[116:119], v228
	ds_read_b128 v[120:123], v228 offset:4096
	ds_read_b128 v[112:115], v224 offset:4096
	s_setprio 1
	v_mfma_f32_32x32x16_bf16 v[50:65], v[126:129], v[134:137], v[50:65]
	v_mfma_f32_32x32x16_bf16 v[18:33], v[126:129], v[138:141], v[18:33]
	v_mfma_f32_32x32x16_bf16 v[34:49], v[130:133], v[134:137], v[34:49]
	v_mfma_f32_32x32x16_bf16 v[2:17], v[130:133], v[138:141], v[2:17]
	s_setprio 0
	ds_read_b128 v[126:129], v225
	ds_read_b128 v[134:137], v229
	ds_read_b128 v[138:141], v229 offset:4096
	ds_read_b128 v[130:133], v225 offset:4096
	s_setprio 1
	s_add_i32 m0, s79, 0xc100
	s_waitcnt lgkmcnt(6)
	v_mfma_f32_32x32x16_bf16 v[50:65], v[108:111], v[116:119], v[50:65]
	global_load_lds_dwordx4 v144, s[72:73]
	s_add_i32 m0, s79, 0xe100
	s_waitcnt lgkmcnt(5)
	v_mfma_f32_32x32x16_bf16 v[18:33], v[108:111], v[120:123], v[18:33]
	global_load_lds_dwordx4 v145, s[72:73]
	s_waitcnt lgkmcnt(4)
	v_mfma_f32_32x32x16_bf16 v[34:49], v[112:115], v[116:119], v[34:49]
	v_mfma_f32_32x32x16_bf16 v[2:17], v[112:115], v[120:123], v[2:17]
	s_setprio 0
	ds_read_b128 v[108:111], v226
	ds_read_b128 v[116:119], v230
	ds_read_b128 v[120:123], v230 offset:4096
	ds_read_b128 v[112:115], v226 offset:4096
	s_setprio 1
	s_add_i32 m0, s79, 0x10100
	s_waitcnt lgkmcnt(6)
	v_mfma_f32_32x32x16_bf16 v[50:65], v[126:129], v[134:137], v[50:65]
	global_load_lds_dwordx4 v144, s[74:75]
	s_add_i32 m0, s79, 0x12100
	s_waitcnt lgkmcnt(5)
	v_mfma_f32_32x32x16_bf16 v[18:33], v[126:129], v[138:141], v[18:33]
	global_load_lds_dwordx4 v145, s[74:75]
	s_waitcnt lgkmcnt(4)
	v_mfma_f32_32x32x16_bf16 v[34:49], v[130:133], v[134:137], v[34:49]
	v_mfma_f32_32x32x16_bf16 v[2:17], v[130:133], v[138:141], v[2:17]
	s_setprio 0
	ds_read_b128 v[126:129], v227
	ds_read_b128 v[134:137], v231
	ds_read_b128 v[138:141], v231 offset:4096
	ds_read_b128 v[130:133], v227 offset:4096
	s_setprio 1
	s_add_i32 m0, s79, 0x14100
	s_waitcnt lgkmcnt(6)
	v_mfma_f32_32x32x16_bf16 v[50:65], v[108:111], v[116:119], v[50:65]
	global_load_lds_dwordx4 v146, s[74:75]
	s_add_i32 m0, s79, 0x16100
	s_waitcnt lgkmcnt(5)
	v_mfma_f32_32x32x16_bf16 v[18:33], v[108:111], v[120:123], v[18:33]
	global_load_lds_dwordx4 v147, s[74:75]
	s_waitcnt lgkmcnt(4)
	v_mfma_f32_32x32x16_bf16 v[34:49], v[112:115], v[116:119], v[34:49]
	v_mfma_f32_32x32x16_bf16 v[2:17], v[112:115], v[120:123], v[2:17]
	s_setprio 0
	s_add_u32 s72, s72, 0x80
	s_addc_u32 s73, s73, 0
	s_add_u32 s74, s74, 0x80
	s_addc_u32 s75, s75, 0
	s_waitcnt lgkmcnt(0)
	s_waitcnt vmcnt(6)
	s_barrier
	ds_read_b128 v[108:111], v216
	ds_read_b128 v[116:119], v220
	ds_read_b128 v[120:123], v220 offset:4096
	ds_read_b128 v[112:115], v216 offset:4096
	s_setprio 1
	v_mfma_f32_32x32x16_bf16 v[50:65], v[126:129], v[134:137], v[50:65]
	v_mfma_f32_32x32x16_bf16 v[18:33], v[126:129], v[138:141], v[18:33]
	v_mfma_f32_32x32x16_bf16 v[34:49], v[130:133], v[134:137], v[34:49]
	v_mfma_f32_32x32x16_bf16 v[2:17], v[130:133], v[138:141], v[2:17]
	s_setprio 0
	ds_read_b128 v[126:129], v217
	ds_read_b128 v[134:137], v221
	ds_read_b128 v[138:141], v221 offset:4096
	ds_read_b128 v[130:133], v217 offset:4096
	s_setprio 1
	s_add_i32 m0, s79, 0x1b900
	s_waitcnt lgkmcnt(6)
	v_mfma_f32_32x32x16_bf16 v[50:65], v[108:111], v[116:119], v[50:65]
	global_load_lds_dwordx4 v144, s[72:73]
	s_add_i32 m0, s79, 0x1d900
	s_waitcnt lgkmcnt(5)
	v_mfma_f32_32x32x16_bf16 v[18:33], v[108:111], v[120:123], v[18:33]
	global_load_lds_dwordx4 v145, s[72:73]
	s_waitcnt lgkmcnt(4)
	v_mfma_f32_32x32x16_bf16 v[34:49], v[112:115], v[116:119], v[34:49]
	v_mfma_f32_32x32x16_bf16 v[2:17], v[112:115], v[120:123], v[2:17]
	s_setprio 0
	ds_read_b128 v[108:111], v218
	ds_read_b128 v[116:119], v222
	ds_read_b128 v[120:123], v222 offset:4096
	ds_read_b128 v[112:115], v218 offset:4096
	s_setprio 1
	s_add_i32 m0, s79, 0x1f900
	s_waitcnt lgkmcnt(6)
	v_mfma_f32_32x32x16_bf16 v[50:65], v[126:129], v[134:137], v[50:65]
	global_load_lds_dwordx4 v144, s[74:75]
	s_add_i32 m0, s79, 0x21900
	s_waitcnt lgkmcnt(5)
	v_mfma_f32_32x32x16_bf16 v[18:33], v[126:129], v[138:141], v[18:33]
	global_load_lds_dwordx4 v145, s[74:75]
	s_waitcnt lgkmcnt(4)
	v_mfma_f32_32x32x16_bf16 v[34:49], v[130:133], v[134:137], v[34:49]
	v_mfma_f32_32x32x16_bf16 v[2:17], v[130:133], v[138:141], v[2:17]
	s_setprio 0
	ds_read_b128 v[126:129], v219
	ds_read_b128 v[134:137], v223
	ds_read_b128 v[138:141], v223 offset:4096
	ds_read_b128 v[130:133], v219 offset:4096
	s_setprio 1
	s_add_i32 m0, s79, 0x23900
	s_waitcnt lgkmcnt(6)
	v_mfma_f32_32x32x16_bf16 v[50:65], v[108:111], v[116:119], v[50:65]
	global_load_lds_dwordx4 v146, s[74:75]
	s_add_i32 m0, s79, 0x25900
	s_waitcnt lgkmcnt(5)
	v_mfma_f32_32x32x16_bf16 v[18:33], v[108:111], v[120:123], v[18:33]
	global_load_lds_dwordx4 v147, s[74:75]
	s_waitcnt lgkmcnt(4)
	v_mfma_f32_32x32x16_bf16 v[34:49], v[112:115], v[116:119], v[34:49]
	v_mfma_f32_32x32x16_bf16 v[2:17], v[112:115], v[120:123], v[2:17]
	s_setprio 0
	s_add_u32 s72, s72, 0x80
	s_addc_u32 s73, s73, 0
	s_add_u32 s74, s74, 0x80
	s_addc_u32 s75, s75, 0
	s_waitcnt lgkmcnt(0)
	s_waitcnt vmcnt(6)
	s_barrier
	ds_read_b128 v[108:111], v216 offset:49152
	ds_read_b128 v[116:119], v220 offset:49152
	ds_read_b128 v[120:123], v220 offset:53248
	ds_read_b128 v[112:115], v216 offset:53248
	s_setprio 1
	v_mfma_f32_32x32x16_bf16 v[50:65], v[126:129], v[134:137], v[50:65]
	v_mfma_f32_32x32x16_bf16 v[18:33], v[126:129], v[138:141], v[18:33]
	v_mfma_f32_32x32x16_bf16 v[34:49], v[130:133], v[134:137], v[34:49]
	v_mfma_f32_32x32x16_bf16 v[2:17], v[130:133], v[138:141], v[2:17]
	s_setprio 0
	ds_read_b128 v[126:129], v217 offset:49152
	ds_read_b128 v[134:137], v221 offset:49152
	ds_read_b128 v[138:141], v221 offset:53248
	ds_read_b128 v[130:133], v217 offset:53248
	s_setprio 1
	s_add_i32 m0, s79, 0x100
	s_waitcnt lgkmcnt(6)
	v_mfma_f32_32x32x16_bf16 v[50:65], v[108:111], v[116:119], v[50:65]
	global_load_lds_dwordx4 v144, s[72:73]
	s_add_i32 m0, s79, 0x2100
	s_waitcnt lgkmcnt(5)
	v_mfma_f32_32x32x16_bf16 v[18:33], v[108:111], v[120:123], v[18:33]
	global_load_lds_dwordx4 v145, s[72:73]
	s_waitcnt lgkmcnt(4)
	v_mfma_f32_32x32x16_bf16 v[34:49], v[112:115], v[116:119], v[34:49]
	v_mfma_f32_32x32x16_bf16 v[2:17], v[112:115], v[120:123], v[2:17]
	s_setprio 0
	ds_read_b128 v[108:111], v218 offset:49152
	ds_read_b128 v[116:119], v222 offset:49152
	ds_read_b128 v[120:123], v222 offset:53248
	ds_read_b128 v[112:115], v218 offset:53248
	s_setprio 1
	s_add_i32 m0, s79, 0x4100
	s_waitcnt lgkmcnt(6)
	v_mfma_f32_32x32x16_bf16 v[50:65], v[126:129], v[134:137], v[50:65]
	global_load_lds_dwordx4 v144, s[74:75]
	s_add_i32 m0, s79, 0x6100
	s_waitcnt lgkmcnt(5)
	v_mfma_f32_32x32x16_bf16 v[18:33], v[126:129], v[138:141], v[18:33]
	global_load_lds_dwordx4 v145, s[74:75]
	s_waitcnt lgkmcnt(4)
	v_mfma_f32_32x32x16_bf16 v[34:49], v[130:133], v[134:137], v[34:49]
	v_mfma_f32_32x32x16_bf16 v[2:17], v[130:133], v[138:141], v[2:17]
	s_setprio 0
	ds_read_b128 v[126:129], v219 offset:49152
	ds_read_b128 v[134:137], v223 offset:49152
	ds_read_b128 v[138:141], v223 offset:53248
	ds_read_b128 v[130:133], v219 offset:53248
	s_setprio 1
	s_add_i32 m0, s79, 0x8100
	s_waitcnt lgkmcnt(6)
	v_mfma_f32_32x32x16_bf16 v[50:65], v[108:111], v[116:119], v[50:65]
	global_load_lds_dwordx4 v146, s[74:75]
	s_add_i32 m0, s79, 0xa100
	s_waitcnt lgkmcnt(5)
	v_mfma_f32_32x32x16_bf16 v[18:33], v[108:111], v[120:123], v[18:33]
	global_load_lds_dwordx4 v147, s[74:75]
	s_waitcnt lgkmcnt(4)
	v_mfma_f32_32x32x16_bf16 v[34:49], v[112:115], v[116:119], v[34:49]
	v_mfma_f32_32x32x16_bf16 v[2:17], v[112:115], v[120:123], v[2:17]
	s_setprio 0
	s_add_u32 s72, s72, 0x80
	s_addc_u32 s73, s73, 0
	s_add_u32 s74, s74, 0x80
	s_addc_u32 s75, s75, 0
	s_waitcnt lgkmcnt(0)
	s_waitcnt vmcnt(6)
	s_barrier
	ds_read_b128 v[108:111], v224
	ds_read_b128 v[116:119], v228
	ds_read_b128 v[120:123], v228 offset:4096
	ds_read_b128 v[112:115], v224 offset:4096
	s_setprio 1
	v_mfma_f32_32x32x16_bf16 v[50:65], v[126:129], v[134:137], v[50:65]
	v_mfma_f32_32x32x16_bf16 v[18:33], v[126:129], v[138:141], v[18:33]
	v_mfma_f32_32x32x16_bf16 v[34:49], v[130:133], v[134:137], v[34:49]
	v_mfma_f32_32x32x16_bf16 v[2:17], v[130:133], v[138:141], v[2:17]
	s_setprio 0
	ds_read_b128 v[126:129], v225
	ds_read_b128 v[134:137], v229
	ds_read_b128 v[138:141], v229 offset:4096
	ds_read_b128 v[130:133], v225 offset:4096
	s_setprio 1
	s_add_i32 m0, s79, 0xc100
	s_waitcnt lgkmcnt(6)
	v_mfma_f32_32x32x16_bf16 v[50:65], v[108:111], v[116:119], v[50:65]
	global_load_lds_dwordx4 v144, s[72:73]
	s_add_i32 m0, s79, 0xe100
	s_waitcnt lgkmcnt(5)
	v_mfma_f32_32x32x16_bf16 v[18:33], v[108:111], v[120:123], v[18:33]
	global_load_lds_dwordx4 v145, s[72:73]
	s_waitcnt lgkmcnt(4)
	v_mfma_f32_32x32x16_bf16 v[34:49], v[112:115], v[116:119], v[34:49]
	v_mfma_f32_32x32x16_bf16 v[2:17], v[112:115], v[120:123], v[2:17]
	s_setprio 0
	ds_read_b128 v[108:111], v226
	ds_read_b128 v[116:119], v230
	ds_read_b128 v[120:123], v230 offset:4096
	ds_read_b128 v[112:115], v226 offset:4096
	s_setprio 1
	s_add_i32 m0, s79, 0x10100
	s_waitcnt lgkmcnt(6)
	v_mfma_f32_32x32x16_bf16 v[50:65], v[126:129], v[134:137], v[50:65]
	global_load_lds_dwordx4 v144, s[74:75]
	s_add_i32 m0, s79, 0x12100
	s_waitcnt lgkmcnt(5)
	v_mfma_f32_32x32x16_bf16 v[18:33], v[126:129], v[138:141], v[18:33]
	global_load_lds_dwordx4 v145, s[74:75]
	s_waitcnt lgkmcnt(4)
	v_mfma_f32_32x32x16_bf16 v[34:49], v[130:133], v[134:137], v[34:49]
	v_mfma_f32_32x32x16_bf16 v[2:17], v[130:133], v[138:141], v[2:17]
	s_setprio 0
	ds_read_b128 v[126:129], v227
	ds_read_b128 v[134:137], v231
	ds_read_b128 v[138:141], v231 offset:4096
	ds_read_b128 v[130:133], v227 offset:4096
	s_setprio 1
	s_add_i32 m0, s79, 0x14100
	s_waitcnt lgkmcnt(6)
	v_mfma_f32_32x32x16_bf16 v[50:65], v[108:111], v[116:119], v[50:65]
	global_load_lds_dwordx4 v146, s[74:75]
	s_add_i32 m0, s79, 0x16100
	s_waitcnt lgkmcnt(5)
	v_mfma_f32_32x32x16_bf16 v[18:33], v[108:111], v[120:123], v[18:33]
	global_load_lds_dwordx4 v147, s[74:75]
	s_waitcnt lgkmcnt(4)
	v_mfma_f32_32x32x16_bf16 v[34:49], v[112:115], v[116:119], v[34:49]
	v_mfma_f32_32x32x16_bf16 v[2:17], v[112:115], v[120:123], v[2:17]
	s_setprio 0
	s_add_u32 s72, s72, 0x80
	s_addc_u32 s73, s73, 0
	s_add_u32 s74, s74, 0x80
	s_addc_u32 s75, s75, 0
	s_waitcnt lgkmcnt(0)
	s_waitcnt vmcnt(6)
	s_barrier
	ds_read_b128 v[108:111], v216
	ds_read_b128 v[116:119], v220
	ds_read_b128 v[120:123], v220 offset:4096
	ds_read_b128 v[112:115], v216 offset:4096
	s_setprio 1
	v_mfma_f32_32x32x16_bf16 v[50:65], v[126:129], v[134:137], v[50:65]
	v_mfma_f32_32x32x16_bf16 v[18:33], v[126:129], v[138:141], v[18:33]
	v_mfma_f32_32x32x16_bf16 v[34:49], v[130:133], v[134:137], v[34:49]
	v_mfma_f32_32x32x16_bf16 v[2:17], v[130:133], v[138:141], v[2:17]
	s_setprio 0
	ds_read_b128 v[126:129], v217
	ds_read_b128 v[134:137], v221
	ds_read_b128 v[138:141], v221 offset:4096
	ds_read_b128 v[130:133], v217 offset:4096
	s_setprio 1
	s_add_i32 m0, s79, 0x1b900
	s_waitcnt lgkmcnt(6)
	v_mfma_f32_32x32x16_bf16 v[50:65], v[108:111], v[116:119], v[50:65]
	global_load_lds_dwordx4 v144, s[72:73]
	s_add_i32 m0, s79, 0x1d900
	s_waitcnt lgkmcnt(5)
	v_mfma_f32_32x32x16_bf16 v[18:33], v[108:111], v[120:123], v[18:33]
	global_load_lds_dwordx4 v145, s[72:73]
	s_waitcnt lgkmcnt(4)
	v_mfma_f32_32x32x16_bf16 v[34:49], v[112:115], v[116:119], v[34:49]
	v_mfma_f32_32x32x16_bf16 v[2:17], v[112:115], v[120:123], v[2:17]
	s_setprio 0
	ds_read_b128 v[108:111], v218
	ds_read_b128 v[116:119], v222
	ds_read_b128 v[120:123], v222 offset:4096
	ds_read_b128 v[112:115], v218 offset:4096
	s_setprio 1
	s_add_i32 m0, s79, 0x1f900
	s_waitcnt lgkmcnt(6)
	v_mfma_f32_32x32x16_bf16 v[50:65], v[126:129], v[134:137], v[50:65]
	global_load_lds_dwordx4 v144, s[74:75]
	s_add_i32 m0, s79, 0x21900
	s_waitcnt lgkmcnt(5)
	v_mfma_f32_32x32x16_bf16 v[18:33], v[126:129], v[138:141], v[18:33]
	global_load_lds_dwordx4 v145, s[74:75]
	s_waitcnt lgkmcnt(4)
	v_mfma_f32_32x32x16_bf16 v[34:49], v[130:133], v[134:137], v[34:49]
	v_mfma_f32_32x32x16_bf16 v[2:17], v[130:133], v[138:141], v[2:17]
	s_setprio 0
	ds_read_b128 v[126:129], v219
	ds_read_b128 v[134:137], v223
	ds_read_b128 v[138:141], v223 offset:4096
	ds_read_b128 v[130:133], v219 offset:4096
	s_setprio 1
	s_add_i32 m0, s79, 0x23900
	s_waitcnt lgkmcnt(6)
	v_mfma_f32_32x32x16_bf16 v[50:65], v[108:111], v[116:119], v[50:65]
	global_load_lds_dwordx4 v146, s[74:75]
	s_add_i32 m0, s79, 0x25900
	s_waitcnt lgkmcnt(5)
	v_mfma_f32_32x32x16_bf16 v[18:33], v[108:111], v[120:123], v[18:33]
	global_load_lds_dwordx4 v147, s[74:75]
	s_waitcnt lgkmcnt(4)
	v_mfma_f32_32x32x16_bf16 v[34:49], v[112:115], v[116:119], v[34:49]
	v_mfma_f32_32x32x16_bf16 v[2:17], v[112:115], v[120:123], v[2:17]
	s_setprio 0
	s_add_u32 s72, s72, 0x80
	s_addc_u32 s73, s73, 0
	s_add_u32 s74, s74, 0x80
	s_addc_u32 s75, s75, 0
	s_waitcnt lgkmcnt(0)
	s_waitcnt vmcnt(6)
	s_barrier
	ds_read_b128 v[108:111], v216 offset:49152
	ds_read_b128 v[116:119], v220 offset:49152
	ds_read_b128 v[120:123], v220 offset:53248
	ds_read_b128 v[112:115], v216 offset:53248
	s_setprio 1
	v_mfma_f32_32x32x16_bf16 v[50:65], v[126:129], v[134:137], v[50:65]
	v_mfma_f32_32x32x16_bf16 v[18:33], v[126:129], v[138:141], v[18:33]
	v_mfma_f32_32x32x16_bf16 v[34:49], v[130:133], v[134:137], v[34:49]
	v_mfma_f32_32x32x16_bf16 v[2:17], v[130:133], v[138:141], v[2:17]
	s_setprio 0
	ds_read_b128 v[126:129], v217 offset:49152
	ds_read_b128 v[134:137], v221 offset:49152
	ds_read_b128 v[138:141], v221 offset:53248
	ds_read_b128 v[130:133], v217 offset:53248
	s_setprio 1
	s_add_i32 m0, s79, 0x100
	s_waitcnt lgkmcnt(6)
	v_mfma_f32_32x32x16_bf16 v[50:65], v[108:111], v[116:119], v[50:65]
	global_load_lds_dwordx4 v144, s[72:73]
	s_add_i32 m0, s79, 0x2100
	s_waitcnt lgkmcnt(5)
	v_mfma_f32_32x32x16_bf16 v[18:33], v[108:111], v[120:123], v[18:33]
	global_load_lds_dwordx4 v145, s[72:73]
	s_waitcnt lgkmcnt(4)
	v_mfma_f32_32x32x16_bf16 v[34:49], v[112:115], v[116:119], v[34:49]
	v_mfma_f32_32x32x16_bf16 v[2:17], v[112:115], v[120:123], v[2:17]
	s_setprio 0
	ds_read_b128 v[108:111], v218 offset:49152
	ds_read_b128 v[116:119], v222 offset:49152
	ds_read_b128 v[120:123], v222 offset:53248
	ds_read_b128 v[112:115], v218 offset:53248
	s_setprio 1
	s_add_i32 m0, s79, 0x4100
	s_waitcnt lgkmcnt(6)
	v_mfma_f32_32x32x16_bf16 v[50:65], v[126:129], v[134:137], v[50:65]
	global_load_lds_dwordx4 v144, s[74:75]
	s_add_i32 m0, s79, 0x6100
	s_waitcnt lgkmcnt(5)
	v_mfma_f32_32x32x16_bf16 v[18:33], v[126:129], v[138:141], v[18:33]
	global_load_lds_dwordx4 v145, s[74:75]
	s_waitcnt lgkmcnt(4)
	v_mfma_f32_32x32x16_bf16 v[34:49], v[130:133], v[134:137], v[34:49]
	v_mfma_f32_32x32x16_bf16 v[2:17], v[130:133], v[138:141], v[2:17]
	s_setprio 0
	ds_read_b128 v[126:129], v219 offset:49152
	ds_read_b128 v[134:137], v223 offset:49152
	ds_read_b128 v[138:141], v223 offset:53248
	ds_read_b128 v[130:133], v219 offset:53248
	s_setprio 1
	s_add_i32 m0, s79, 0x8100
	s_waitcnt lgkmcnt(6)
	v_mfma_f32_32x32x16_bf16 v[50:65], v[108:111], v[116:119], v[50:65]
	global_load_lds_dwordx4 v146, s[74:75]
	s_add_i32 m0, s79, 0xa100
	s_waitcnt lgkmcnt(5)
	v_mfma_f32_32x32x16_bf16 v[18:33], v[108:111], v[120:123], v[18:33]
	global_load_lds_dwordx4 v147, s[74:75]
	s_waitcnt lgkmcnt(4)
	v_mfma_f32_32x32x16_bf16 v[34:49], v[112:115], v[116:119], v[34:49]
	v_mfma_f32_32x32x16_bf16 v[2:17], v[112:115], v[120:123], v[2:17]
	s_setprio 0
	s_add_u32 s72, s72, 0x80
	s_addc_u32 s73, s73, 0
	s_add_u32 s74, s74, 0x80
	s_addc_u32 s75, s75, 0
	s_waitcnt lgkmcnt(0)
	s_waitcnt vmcnt(6)
	s_barrier
	ds_read_b128 v[108:111], v224
	ds_read_b128 v[116:119], v228
	ds_read_b128 v[120:123], v228 offset:4096
	ds_read_b128 v[112:115], v224 offset:4096
	s_setprio 1
	v_mfma_f32_32x32x16_bf16 v[50:65], v[126:129], v[134:137], v[50:65]
	v_mfma_f32_32x32x16_bf16 v[18:33], v[126:129], v[138:141], v[18:33]
	v_mfma_f32_32x32x16_bf16 v[34:49], v[130:133], v[134:137], v[34:49]
	v_mfma_f32_32x32x16_bf16 v[2:17], v[130:133], v[138:141], v[2:17]
	s_setprio 0
	ds_read_b128 v[126:129], v225
	ds_read_b128 v[134:137], v229
	ds_read_b128 v[138:141], v229 offset:4096
	ds_read_b128 v[130:133], v225 offset:4096
	s_setprio 1
	s_add_i32 m0, s79, 0xc100
	s_waitcnt lgkmcnt(6)
	v_mfma_f32_32x32x16_bf16 v[50:65], v[108:111], v[116:119], v[50:65]
	global_load_lds_dwordx4 v144, s[72:73]
	s_add_i32 m0, s79, 0xe100
	s_waitcnt lgkmcnt(5)
	v_mfma_f32_32x32x16_bf16 v[18:33], v[108:111], v[120:123], v[18:33]
	global_load_lds_dwordx4 v145, s[72:73]
	s_waitcnt lgkmcnt(4)
	v_mfma_f32_32x32x16_bf16 v[34:49], v[112:115], v[116:119], v[34:49]
	v_mfma_f32_32x32x16_bf16 v[2:17], v[112:115], v[120:123], v[2:17]
	s_setprio 0
	ds_read_b128 v[108:111], v226
	ds_read_b128 v[116:119], v230
	ds_read_b128 v[120:123], v230 offset:4096
	ds_read_b128 v[112:115], v226 offset:4096
	s_setprio 1
	s_add_i32 m0, s79, 0x10100
	s_waitcnt lgkmcnt(6)
	v_mfma_f32_32x32x16_bf16 v[50:65], v[126:129], v[134:137], v[50:65]
	global_load_lds_dwordx4 v144, s[74:75]
	s_add_i32 m0, s79, 0x12100
	s_waitcnt lgkmcnt(5)
	v_mfma_f32_32x32x16_bf16 v[18:33], v[126:129], v[138:141], v[18:33]
	global_load_lds_dwordx4 v145, s[74:75]
	s_waitcnt lgkmcnt(4)
	v_mfma_f32_32x32x16_bf16 v[34:49], v[130:133], v[134:137], v[34:49]
	v_mfma_f32_32x32x16_bf16 v[2:17], v[130:133], v[138:141], v[2:17]
	s_setprio 0
	ds_read_b128 v[126:129], v227
	ds_read_b128 v[134:137], v231
	ds_read_b128 v[138:141], v231 offset:4096
	ds_read_b128 v[130:133], v227 offset:4096
	s_setprio 1
	s_add_i32 m0, s79, 0x14100
	s_waitcnt lgkmcnt(6)
	v_mfma_f32_32x32x16_bf16 v[50:65], v[108:111], v[116:119], v[50:65]
	global_load_lds_dwordx4 v146, s[74:75]
	s_add_i32 m0, s79, 0x16100
	s_waitcnt lgkmcnt(5)
	v_mfma_f32_32x32x16_bf16 v[18:33], v[108:111], v[120:123], v[18:33]
	global_load_lds_dwordx4 v147, s[74:75]
	s_waitcnt lgkmcnt(4)
	v_mfma_f32_32x32x16_bf16 v[34:49], v[112:115], v[116:119], v[34:49]
	v_mfma_f32_32x32x16_bf16 v[2:17], v[112:115], v[120:123], v[2:17]
	s_setprio 0
	s_add_u32 s72, s72, 0x80
	s_addc_u32 s73, s73, 0
	s_add_u32 s74, s74, 0x80
	s_addc_u32 s75, s75, 0
	s_waitcnt lgkmcnt(0)
	s_waitcnt vmcnt(6)
	s_barrier
	ds_read_b128 v[108:111], v216
	ds_read_b128 v[116:119], v220
	ds_read_b128 v[120:123], v220 offset:4096
	ds_read_b128 v[112:115], v216 offset:4096
	s_setprio 1
	v_mfma_f32_32x32x16_bf16 v[50:65], v[126:129], v[134:137], v[50:65]
	v_mfma_f32_32x32x16_bf16 v[18:33], v[126:129], v[138:141], v[18:33]
	v_mfma_f32_32x32x16_bf16 v[34:49], v[130:133], v[134:137], v[34:49]
	v_mfma_f32_32x32x16_bf16 v[2:17], v[130:133], v[138:141], v[2:17]
	s_setprio 0
	ds_read_b128 v[126:129], v217
	ds_read_b128 v[134:137], v221
	ds_read_b128 v[138:141], v221 offset:4096
	ds_read_b128 v[130:133], v217 offset:4096
	s_setprio 1
	s_add_i32 m0, s79, 0x1b900
	s_waitcnt lgkmcnt(6)
	v_mfma_f32_32x32x16_bf16 v[50:65], v[108:111], v[116:119], v[50:65]
	global_load_lds_dwordx4 v144, s[72:73]
	s_add_i32 m0, s79, 0x1d900
	s_waitcnt lgkmcnt(5)
	v_mfma_f32_32x32x16_bf16 v[18:33], v[108:111], v[120:123], v[18:33]
	global_load_lds_dwordx4 v145, s[72:73]
	s_waitcnt lgkmcnt(4)
	v_mfma_f32_32x32x16_bf16 v[34:49], v[112:115], v[116:119], v[34:49]
	v_mfma_f32_32x32x16_bf16 v[2:17], v[112:115], v[120:123], v[2:17]
	s_setprio 0
	ds_read_b128 v[108:111], v218
	ds_read_b128 v[116:119], v222
	ds_read_b128 v[120:123], v222 offset:4096
	ds_read_b128 v[112:115], v218 offset:4096
	s_setprio 1
	s_add_i32 m0, s79, 0x1f900
	s_waitcnt lgkmcnt(6)
	v_mfma_f32_32x32x16_bf16 v[50:65], v[126:129], v[134:137], v[50:65]
	global_load_lds_dwordx4 v144, s[74:75]
	s_add_i32 m0, s79, 0x21900
	s_waitcnt lgkmcnt(5)
	v_mfma_f32_32x32x16_bf16 v[18:33], v[126:129], v[138:141], v[18:33]
	global_load_lds_dwordx4 v145, s[74:75]
	s_waitcnt lgkmcnt(4)
	v_mfma_f32_32x32x16_bf16 v[34:49], v[130:133], v[134:137], v[34:49]
	v_mfma_f32_32x32x16_bf16 v[2:17], v[130:133], v[138:141], v[2:17]
	s_setprio 0
	ds_read_b128 v[126:129], v219
	ds_read_b128 v[134:137], v223
	ds_read_b128 v[138:141], v223 offset:4096
	ds_read_b128 v[130:133], v219 offset:4096
	s_setprio 1
	s_add_i32 m0, s79, 0x23900
	s_waitcnt lgkmcnt(6)
	v_mfma_f32_32x32x16_bf16 v[50:65], v[108:111], v[116:119], v[50:65]
	global_load_lds_dwordx4 v146, s[74:75]
	s_add_i32 m0, s79, 0x25900
	s_waitcnt lgkmcnt(5)
	v_mfma_f32_32x32x16_bf16 v[18:33], v[108:111], v[120:123], v[18:33]
	global_load_lds_dwordx4 v147, s[74:75]
	s_waitcnt lgkmcnt(4)
	v_mfma_f32_32x32x16_bf16 v[34:49], v[112:115], v[116:119], v[34:49]
	v_mfma_f32_32x32x16_bf16 v[2:17], v[112:115], v[120:123], v[2:17]
	s_setprio 0
	s_add_u32 s72, s72, 0x80
	s_addc_u32 s73, s73, 0
	s_add_u32 s74, s74, 0x80
	s_addc_u32 s75, s75, 0
	s_waitcnt lgkmcnt(0)
	s_waitcnt vmcnt(6)
	s_barrier
	ds_read_b128 v[108:111], v216 offset:49152
	ds_read_b128 v[116:119], v220 offset:49152
	ds_read_b128 v[120:123], v220 offset:53248
	ds_read_b128 v[112:115], v216 offset:53248
	s_setprio 1
	v_mfma_f32_32x32x16_bf16 v[50:65], v[126:129], v[134:137], v[50:65]
	v_mfma_f32_32x32x16_bf16 v[18:33], v[126:129], v[138:141], v[18:33]
	v_mfma_f32_32x32x16_bf16 v[34:49], v[130:133], v[134:137], v[34:49]
	v_mfma_f32_32x32x16_bf16 v[2:17], v[130:133], v[138:141], v[2:17]
	s_setprio 0
	ds_read_b128 v[126:129], v217 offset:49152
	ds_read_b128 v[134:137], v221 offset:49152
	ds_read_b128 v[138:141], v221 offset:53248
	ds_read_b128 v[130:133], v217 offset:53248
	s_setprio 1
	s_add_i32 m0, s79, 0x100
	s_waitcnt lgkmcnt(6)
	v_mfma_f32_32x32x16_bf16 v[50:65], v[108:111], v[116:119], v[50:65]
	global_load_lds_dwordx4 v144, s[72:73]
	s_add_i32 m0, s79, 0x2100
	s_waitcnt lgkmcnt(5)
	v_mfma_f32_32x32x16_bf16 v[18:33], v[108:111], v[120:123], v[18:33]
	global_load_lds_dwordx4 v145, s[72:73]
	s_waitcnt lgkmcnt(4)
	v_mfma_f32_32x32x16_bf16 v[34:49], v[112:115], v[116:119], v[34:49]
	v_mfma_f32_32x32x16_bf16 v[2:17], v[112:115], v[120:123], v[2:17]
	s_setprio 0
	ds_read_b128 v[108:111], v218 offset:49152
	ds_read_b128 v[116:119], v222 offset:49152
	ds_read_b128 v[120:123], v222 offset:53248
	ds_read_b128 v[112:115], v218 offset:53248
	s_setprio 1
	s_add_i32 m0, s79, 0x4100
	s_waitcnt lgkmcnt(6)
	v_mfma_f32_32x32x16_bf16 v[50:65], v[126:129], v[134:137], v[50:65]
	global_load_lds_dwordx4 v144, s[74:75]
	s_add_i32 m0, s79, 0x6100
	s_waitcnt lgkmcnt(5)
	v_mfma_f32_32x32x16_bf16 v[18:33], v[126:129], v[138:141], v[18:33]
	global_load_lds_dwordx4 v145, s[74:75]
	s_waitcnt lgkmcnt(4)
	v_mfma_f32_32x32x16_bf16 v[34:49], v[130:133], v[134:137], v[34:49]
	v_mfma_f32_32x32x16_bf16 v[2:17], v[130:133], v[138:141], v[2:17]
	s_setprio 0
	ds_read_b128 v[126:129], v219 offset:49152
	ds_read_b128 v[134:137], v223 offset:49152
	ds_read_b128 v[138:141], v223 offset:53248
	ds_read_b128 v[130:133], v219 offset:53248
	s_setprio 1
	s_add_i32 m0, s79, 0x8100
	s_waitcnt lgkmcnt(6)
	v_mfma_f32_32x32x16_bf16 v[50:65], v[108:111], v[116:119], v[50:65]
	global_load_lds_dwordx4 v146, s[74:75]
	s_add_i32 m0, s79, 0xa100
	s_waitcnt lgkmcnt(5)
	v_mfma_f32_32x32x16_bf16 v[18:33], v[108:111], v[120:123], v[18:33]
	global_load_lds_dwordx4 v147, s[74:75]
	s_waitcnt lgkmcnt(4)
	v_mfma_f32_32x32x16_bf16 v[34:49], v[112:115], v[116:119], v[34:49]
	v_mfma_f32_32x32x16_bf16 v[2:17], v[112:115], v[120:123], v[2:17]
	s_setprio 0
	s_add_u32 s72, s72, 0x80
	s_addc_u32 s73, s73, 0
	s_add_u32 s74, s74, 0x80
	s_addc_u32 s75, s75, 0
	s_waitcnt lgkmcnt(0)
	s_waitcnt vmcnt(6)
	s_barrier
	ds_read_b128 v[108:111], v224
	ds_read_b128 v[116:119], v228
	ds_read_b128 v[120:123], v228 offset:4096
	ds_read_b128 v[112:115], v224 offset:4096
	s_setprio 1
	v_mfma_f32_32x32x16_bf16 v[50:65], v[126:129], v[134:137], v[50:65]
	v_mfma_f32_32x32x16_bf16 v[18:33], v[126:129], v[138:141], v[18:33]
	v_mfma_f32_32x32x16_bf16 v[34:49], v[130:133], v[134:137], v[34:49]
	v_mfma_f32_32x32x16_bf16 v[2:17], v[130:133], v[138:141], v[2:17]
	s_setprio 0
	ds_read_b128 v[126:129], v225
	ds_read_b128 v[134:137], v229
	ds_read_b128 v[138:141], v229 offset:4096
	ds_read_b128 v[130:133], v225 offset:4096
	s_setprio 1
	s_waitcnt lgkmcnt(6)
	v_mfma_f32_32x32x16_bf16 v[50:65], v[108:111], v[116:119], v[50:65]
	s_waitcnt lgkmcnt(5)
	v_mfma_f32_32x32x16_bf16 v[18:33], v[108:111], v[120:123], v[18:33]
	s_waitcnt lgkmcnt(4)
	v_mfma_f32_32x32x16_bf16 v[34:49], v[112:115], v[116:119], v[34:49]
	v_mfma_f32_32x32x16_bf16 v[2:17], v[112:115], v[120:123], v[2:17]
	s_setprio 0
	ds_read_b128 v[108:111], v226
	ds_read_b128 v[116:119], v230
	ds_read_b128 v[120:123], v230 offset:4096
	ds_read_b128 v[112:115], v226 offset:4096
	s_setprio 1
	s_waitcnt lgkmcnt(6)
	v_mfma_f32_32x32x16_bf16 v[50:65], v[126:129], v[134:137], v[50:65]
	s_waitcnt lgkmcnt(5)
	v_mfma_f32_32x32x16_bf16 v[18:33], v[126:129], v[138:141], v[18:33]
	s_waitcnt lgkmcnt(4)
	v_mfma_f32_32x32x16_bf16 v[34:49], v[130:133], v[134:137], v[34:49]
	v_mfma_f32_32x32x16_bf16 v[2:17], v[130:133], v[138:141], v[2:17]
	s_setprio 0
	ds_read_b128 v[126:129], v227
	ds_read_b128 v[134:137], v231
	ds_read_b128 v[138:141], v231 offset:4096
	ds_read_b128 v[130:133], v227 offset:4096
	s_setprio 1
	s_waitcnt lgkmcnt(6)
	v_mfma_f32_32x32x16_bf16 v[50:65], v[108:111], v[116:119], v[50:65]
	s_waitcnt lgkmcnt(5)
	v_mfma_f32_32x32x16_bf16 v[18:33], v[108:111], v[120:123], v[18:33]
	s_waitcnt lgkmcnt(4)
	v_mfma_f32_32x32x16_bf16 v[34:49], v[112:115], v[116:119], v[34:49]
	v_mfma_f32_32x32x16_bf16 v[2:17], v[112:115], v[120:123], v[2:17]
	s_setprio 0
	s_waitcnt lgkmcnt(0)
	s_waitcnt vmcnt(0)
	s_barrier
	ds_read_b128 v[108:111], v216
	ds_read_b128 v[116:119], v220
	ds_read_b128 v[120:123], v220 offset:4096
	ds_read_b128 v[112:115], v216 offset:4096
	s_setprio 1
	v_mfma_f32_32x32x16_bf16 v[50:65], v[126:129], v[134:137], v[50:65]
	v_mfma_f32_32x32x16_bf16 v[18:33], v[126:129], v[138:141], v[18:33]
	v_mfma_f32_32x32x16_bf16 v[34:49], v[130:133], v[134:137], v[34:49]
	v_mfma_f32_32x32x16_bf16 v[2:17], v[130:133], v[138:141], v[2:17]
	s_setprio 0
	ds_read_b128 v[126:129], v217
	ds_read_b128 v[134:137], v221
	ds_read_b128 v[138:141], v221 offset:4096
	ds_read_b128 v[130:133], v217 offset:4096
	s_setprio 1
	s_waitcnt lgkmcnt(6)
	v_mfma_f32_32x32x16_bf16 v[50:65], v[108:111], v[116:119], v[50:65]
	s_waitcnt lgkmcnt(5)
	v_mfma_f32_32x32x16_bf16 v[18:33], v[108:111], v[120:123], v[18:33]
	s_waitcnt lgkmcnt(4)
	v_mfma_f32_32x32x16_bf16 v[34:49], v[112:115], v[116:119], v[34:49]
	v_mfma_f32_32x32x16_bf16 v[2:17], v[112:115], v[120:123], v[2:17]
	s_setprio 0
	ds_read_b128 v[108:111], v218
	ds_read_b128 v[116:119], v222
	ds_read_b128 v[120:123], v222 offset:4096
	ds_read_b128 v[112:115], v218 offset:4096
	s_setprio 1
	s_waitcnt lgkmcnt(6)
	v_mfma_f32_32x32x16_bf16 v[50:65], v[126:129], v[134:137], v[50:65]
	s_waitcnt lgkmcnt(5)
	v_mfma_f32_32x32x16_bf16 v[18:33], v[126:129], v[138:141], v[18:33]
	s_waitcnt lgkmcnt(4)
	v_mfma_f32_32x32x16_bf16 v[34:49], v[130:133], v[134:137], v[34:49]
	v_mfma_f32_32x32x16_bf16 v[2:17], v[130:133], v[138:141], v[2:17]
	s_setprio 0
	ds_read_b128 v[126:129], v219
	ds_read_b128 v[134:137], v223
	ds_read_b128 v[138:141], v223 offset:4096
	ds_read_b128 v[130:133], v219 offset:4096
	s_setprio 1
	s_waitcnt lgkmcnt(6)
	v_mfma_f32_32x32x16_bf16 v[50:65], v[108:111], v[116:119], v[50:65]
	s_waitcnt lgkmcnt(5)
	v_mfma_f32_32x32x16_bf16 v[18:33], v[108:111], v[120:123], v[18:33]
	s_waitcnt lgkmcnt(4)
	v_mfma_f32_32x32x16_bf16 v[34:49], v[112:115], v[116:119], v[34:49]
	v_mfma_f32_32x32x16_bf16 v[2:17], v[112:115], v[120:123], v[2:17]
	s_setprio 0
	s_waitcnt lgkmcnt(0)
	s_waitcnt vmcnt(0)
	s_barrier

.Lg2_ptr:
	s_load_dwordx2 s[30:31], s[34:35], 0x0
	v_readfirstlane_b32 s34, v184
	s_nop 3
	s_lshr_b32 s6, s34, 4
	s_and_b32 s6, s6, 4
	v_bitop3_b32 v6, s6, v208, v209 bitop3:0x36
	v_lshl_or_b32 v2, s49, 3, v210
	v_lshlrev_b32_e32 v2, 11, v2
	v_lshlrev_b32_e32 v6, 4, v6
	v_or_b32_e32 v124, v2, v6
	v_add_u32_e32 v125, 0x20000, v124
	v_add_u32_e32 v126, 0x40000, v124
	v_add_u32_e32 v127, 0x60000, v124
	s_lshl_b32 s19, s49, 10
	s_and_b32 s6, s34, 64
	v_or_b32_e32 v2, s6, v189
	v_lshlrev_b32_e32 v118, 7, v2
	s_lshr_b32 s6, s34, 1
	s_and_b32 s50, s6, 0x7fffffc0
	v_or_b32_e32 v2, s50, v189
	v_lshlrev_b32_e32 v119, 7, v2
	s_mulk_i32 s49, 0x3000
	s_add_i32 s34, s49, 0x100
	v_add3_u32 v240, s34, v72, v74
	v_add3_u32 v83, s34, v187, v73
	s_add_i32 s4, s50, s48
	v_add_u32_e32 v216, s4, v75
	v_add_u32_e32 v217, s4, v76
	v_add_u32_e32 v218, s4, v77
	v_add_u32_e32 v219, s4, v78
	v_add_u32_e32 v220, s4, v79
	v_add_u32_e32 v221, s4, v80
	v_add_u32_e32 v222, s4, v81
	v_add_u32_e32 v223, s4, v82
	v_lshlrev_b32_e32 v216, 2, v216
	v_lshlrev_b32_e32 v217, 2, v217
	v_lshlrev_b32_e32 v218, 2, v218
	v_lshlrev_b32_e32 v219, 2, v219
	v_lshlrev_b32_e32 v220, 2, v220
	v_lshlrev_b32_e32 v221, 2, v221
	v_lshlrev_b32_e32 v222, 2, v222
	v_lshlrev_b32_e32 v223, 2, v223
	v_lshlrev_b32_e32 v68, 2, v188
	s_lshl_b64 s[28:29], s[28:29], 2
	s_add_u32 s6, s54, s28
	s_addc_u32 s7, s55, s29
	s_lshl_b64 s[28:29], s[4:5], 2
	s_add_u32 s28, s6, s28
	s_addc_u32 s29, s7, s29
	v_lshl_add_u64 v[64:65], s[28:29], 0, v[68:69]
	v_add_co_u32_e32 v64, vcc, s46, v64
	s_nop 1
	v_addc_co_u32_e32 v65, vcc, 0, v65, vcc
	s_waitcnt lgkmcnt(0)
	s_add_u32 s26, s30, s26
	s_addc_u32 s27, s31, s27
	s_add_u32 s8, s26, 0x20000
	s_addc_u32 s9, s27, 0
	s_add_u32 s10, s24, 0x20000
	s_addc_u32 s11, s25, 0
	s_add_i32 m0, s19, 0x100
	s_nop 0
	global_load_lds_dwordx4 v124, s[12:13]
	s_add_i32 m0, s19, 0x2100
	s_nop 0
	global_load_lds_dwordx4 v125, s[12:13]
	s_add_i32 m0, s19, 0x4100
	s_nop 0
	global_load_lds_dwordx4 v124, s[14:15]
	s_add_i32 m0, s19, 0x6100
	s_nop 0
	global_load_lds_dwordx4 v125, s[14:15]
	s_add_i32 m0, s19, 0x8100
	s_nop 0
	global_load_lds_dwordx4 v126, s[14:15]
	s_add_i32 m0, s19, 0xa100
	s_nop 0
	global_load_lds_dwordx4 v127, s[14:15]
	s_add_u32 s12, s12, 0x80
	s_addc_u32 s13, s13, 0
	s_add_u32 s14, s14, 0x80
	s_addc_u32 s15, s15, 0
	s_add_i32 m0, s19, 0xc100
	s_nop 0
	global_load_lds_dwordx4 v124, s[12:13]
	s_add_i32 m0, s19, 0xe100
	s_nop 0
	global_load_lds_dwordx4 v125, s[12:13]
	s_add_i32 m0, s19, 0x10100
	s_nop 0
	global_load_lds_dwordx4 v124, s[14:15]
	s_add_i32 m0, s19, 0x12100
	s_nop 0
	global_load_lds_dwordx4 v125, s[14:15]
	s_add_i32 m0, s19, 0x14100
	s_nop 0
	global_load_lds_dwordx4 v126, s[14:15]
	s_add_i32 m0, s19, 0x16100
	s_nop 0
	global_load_lds_dwordx4 v127, s[14:15]
	s_add_u32 s12, s12, 0x80
	s_addc_u32 s13, s13, 0
	s_add_u32 s14, s14, 0x80
	s_addc_u32 s15, s15, 0
	global_load_dwordx4 v[64:67], v[64:65], off
	global_load_dwordx4 v[128:131], v216, s[26:27]
	global_load_dwordx4 v[132:135], v217, s[26:27]
	global_load_dwordx4 v[136:139], v218, s[26:27]
	global_load_dwordx4 v[140:143], v219, s[26:27]
	global_load_dwordx4 v[144:147], v220, s[26:27]
	global_load_dwordx4 v[148:151], v221, s[26:27]
	global_load_dwordx4 v[152:155], v222, s[26:27]
	global_load_dwordx4 v[156:159], v223, s[26:27]
	global_load_dwordx4 v[160:163], v216, s[8:9]
	global_load_dwordx4 v[164:167], v217, s[8:9]
	global_load_dwordx4 v[168:171], v218, s[8:9]
	global_load_dwordx4 v[172:175], v219, s[8:9]
	global_load_dwordx4 v[176:179], v220, s[8:9]
	global_load_dwordx4 v[180:183], v221, s[8:9]
	global_load_dwordx4 v[190:193], v222, s[8:9]
	global_load_dwordx4 v[194:197], v223, s[8:9]
	s_movk_i32 s21, 0x100
	v_add3_u32 v224, s21, v118, v211
	v_add3_u32 v225, s21, v118, v212
	v_add3_u32 v226, s21, v118, v213
	v_add3_u32 v227, s21, v118, v214
	s_movk_i32 s21, 0x4100
	v_add3_u32 v228, s21, v119, v211
	v_add3_u32 v229, s21, v119, v212
	v_add3_u32 v230, s21, v119, v213
	v_add3_u32 v231, s21, v119, v214
	s_mov_b32 s21, 0x1b800
	v_add_u32_e32 v232, s21, v224
	v_add_u32_e32 v236, s21, v228
	v_add_u32_e32 v233, s21, v225
	v_add_u32_e32 v237, s21, v229
	v_add_u32_e32 v234, s21, v226
	v_add_u32_e32 v238, s21, v230
	v_add_u32_e32 v235, s21, v227
	v_add_u32_e32 v239, s21, v231
	s_waitcnt vmcnt(23)
	s_barrier
	ds_read_b128 v[84:87], v224
	ds_read_b128 v[92:95], v228
	ds_read_b128 v[96:99], v228 offset:4096
	ds_read_b128 v[88:91], v224 offset:4096
.Lg2_loop:
	ds_read_b128 v[102:105], v225
	ds_read_b128 v[110:113], v229
	ds_read_b128 v[114:117], v229 offset:4096
	ds_read_b128 v[106:109], v225 offset:4096
	s_setprio 1
	s_add_i32 m0, s19, 0x1b900
	s_waitcnt lgkmcnt(6)
	v_mfma_f32_32x32x16_bf16 v[48:63], v[84:87], v[92:95], 0
	global_load_lds_dwordx4 v124, s[12:13]
	s_add_i32 m0, s19, 0x1d900
	s_waitcnt lgkmcnt(5)
	v_mfma_f32_32x32x16_bf16 v[32:47], v[84:87], v[96:99], 0
	global_load_lds_dwordx4 v125, s[12:13]
	s_waitcnt lgkmcnt(4)
	v_mfma_f32_32x32x16_bf16 v[16:31], v[88:91], v[92:95], 0
	v_mfma_f32_32x32x16_bf16 v[0:15], v[88:91], v[96:99], 0
	s_setprio 0
	ds_read_b128 v[84:87], v226
	ds_read_b128 v[92:95], v230
	ds_read_b128 v[96:99], v230 offset:4096
	ds_read_b128 v[88:91], v226 offset:4096
	s_setprio 1
	s_add_i32 m0, s19, 0x1f900
	s_waitcnt lgkmcnt(6)
	v_mfma_f32_32x32x16_bf16 v[48:63], v[102:105], v[110:113], v[48:63]
	global_load_lds_dwordx4 v124, s[14:15]
	s_add_i32 m0, s19, 0x21900
	s_waitcnt lgkmcnt(5)
	v_mfma_f32_32x32x16_bf16 v[32:47], v[102:105], v[114:117], v[32:47]
	global_load_lds_dwordx4 v125, s[14:15]
	s_waitcnt lgkmcnt(4)
	v_mfma_f32_32x32x16_bf16 v[16:31], v[106:109], v[110:113], v[16:31]
	v_mfma_f32_32x32x16_bf16 v[0:15], v[106:109], v[114:117], v[0:15]
	s_setprio 0
	ds_read_b128 v[102:105], v227
	ds_read_b128 v[110:113], v231
	ds_read_b128 v[114:117], v231 offset:4096
	ds_read_b128 v[106:109], v227 offset:4096
	s_setprio 1
	s_add_i32 m0, s19, 0x23900
	s_waitcnt lgkmcnt(6)
	v_mfma_f32_32x32x16_bf16 v[48:63], v[84:87], v[92:95], v[48:63]
	global_load_lds_dwordx4 v126, s[14:15]
	s_add_i32 m0, s19, 0x25900
	s_waitcnt lgkmcnt(5)
	v_mfma_f32_32x32x16_bf16 v[32:47], v[84:87], v[96:99], v[32:47]
	global_load_lds_dwordx4 v127, s[14:15]
	s_waitcnt lgkmcnt(4)
	v_mfma_f32_32x32x16_bf16 v[16:31], v[88:91], v[92:95], v[16:31]
	v_mfma_f32_32x32x16_bf16 v[0:15], v[88:91], v[96:99], v[0:15]
	s_setprio 0
	s_add_u32 s12, s12, 0x80
	s_addc_u32 s13, s13, 0
	s_add_u32 s14, s14, 0x80
	s_addc_u32 s15, s15, 0
	s_waitcnt lgkmcnt(0)
	s_waitcnt vmcnt(23)
	s_barrier
	ds_read_b128 v[84:87], v224 offset:49152
	ds_read_b128 v[92:95], v228 offset:49152
	ds_read_b128 v[96:99], v228 offset:53248
	ds_read_b128 v[88:91], v224 offset:53248
	s_setprio 1
	v_mfma_f32_32x32x16_bf16 v[48:63], v[102:105], v[110:113], v[48:63]
	v_mfma_f32_32x32x16_bf16 v[32:47], v[102:105], v[114:117], v[32:47]
	v_mfma_f32_32x32x16_bf16 v[16:31], v[106:109], v[110:113], v[16:31]
	v_mfma_f32_32x32x16_bf16 v[0:15], v[106:109], v[114:117], v[0:15]
	s_setprio 0
	ds_read_b128 v[102:105], v225 offset:49152
	ds_read_b128 v[110:113], v229 offset:49152
	ds_read_b128 v[114:117], v229 offset:53248
	ds_read_b128 v[106:109], v225 offset:53248
	s_setprio 1
	s_add_i32 m0, s19, 0x100
	s_waitcnt lgkmcnt(6)
	v_mfma_f32_32x32x16_bf16 v[48:63], v[84:87], v[92:95], v[48:63]
	global_load_lds_dwordx4 v124, s[12:13]
	s_add_i32 m0, s19, 0x2100
	s_waitcnt lgkmcnt(5)
	v_mfma_f32_32x32x16_bf16 v[32:47], v[84:87], v[96:99], v[32:47]
	global_load_lds_dwordx4 v125, s[12:13]
	s_waitcnt lgkmcnt(4)
	v_mfma_f32_32x32x16_bf16 v[16:31], v[88:91], v[92:95], v[16:31]
	v_mfma_f32_32x32x16_bf16 v[0:15], v[88:91], v[96:99], v[0:15]
	s_setprio 0
	ds_read_b128 v[84:87], v226 offset:49152
	ds_read_b128 v[92:95], v230 offset:49152
	ds_read_b128 v[96:99], v230 offset:53248
	ds_read_b128 v[88:91], v226 offset:53248
	s_setprio 1
	s_add_i32 m0, s19, 0x4100
	s_waitcnt lgkmcnt(6)
	v_mfma_f32_32x32x16_bf16 v[48:63], v[102:105], v[110:113], v[48:63]
	global_load_lds_dwordx4 v124, s[14:15]
	s_add_i32 m0, s19, 0x6100
	s_waitcnt lgkmcnt(5)
	v_mfma_f32_32x32x16_bf16 v[32:47], v[102:105], v[114:117], v[32:47]
	global_load_lds_dwordx4 v125, s[14:15]
	s_waitcnt lgkmcnt(4)
	v_mfma_f32_32x32x16_bf16 v[16:31], v[106:109], v[110:113], v[16:31]
	v_mfma_f32_32x32x16_bf16 v[0:15], v[106:109], v[114:117], v[0:15]
	s_setprio 0
	ds_read_b128 v[102:105], v227 offset:49152
	ds_read_b128 v[110:113], v231 offset:49152
	ds_read_b128 v[114:117], v231 offset:53248
	ds_read_b128 v[106:109], v227 offset:53248
	s_setprio 1
	s_add_i32 m0, s19, 0x8100
	s_waitcnt lgkmcnt(6)
	v_mfma_f32_32x32x16_bf16 v[48:63], v[84:87], v[92:95], v[48:63]
	global_load_lds_dwordx4 v126, s[14:15]
	s_add_i32 m0, s19, 0xa100
	s_waitcnt lgkmcnt(5)
	v_mfma_f32_32x32x16_bf16 v[32:47], v[84:87], v[96:99], v[32:47]
	global_load_lds_dwordx4 v127, s[14:15]
	s_waitcnt lgkmcnt(4)
	v_mfma_f32_32x32x16_bf16 v[16:31], v[88:91], v[92:95], v[16:31]
	v_mfma_f32_32x32x16_bf16 v[0:15], v[88:91], v[96:99], v[0:15]
	s_setprio 0
	s_add_u32 s12, s12, 0x80
	s_addc_u32 s13, s13, 0
	s_add_u32 s14, s14, 0x80
	s_addc_u32 s15, s15, 0
	s_waitcnt lgkmcnt(0)
	s_waitcnt vmcnt(6)
	s_barrier
	ds_read_b128 v[84:87], v232
	ds_read_b128 v[92:95], v236
	ds_read_b128 v[96:99], v236 offset:4096
	ds_read_b128 v[88:91], v232 offset:4096
	s_setprio 1
	v_mfma_f32_32x32x16_bf16 v[48:63], v[102:105], v[110:113], v[48:63]
	v_mfma_f32_32x32x16_bf16 v[32:47], v[102:105], v[114:117], v[32:47]
	v_mfma_f32_32x32x16_bf16 v[16:31], v[106:109], v[110:113], v[16:31]
	v_mfma_f32_32x32x16_bf16 v[0:15], v[106:109], v[114:117], v[0:15]
	s_setprio 0
	ds_read_b128 v[102:105], v233
	ds_read_b128 v[110:113], v237
	ds_read_b128 v[114:117], v237 offset:4096
	ds_read_b128 v[106:109], v233 offset:4096
	s_setprio 1
	s_add_i32 m0, s19, 0xc100
	s_waitcnt lgkmcnt(6)
	v_mfma_f32_32x32x16_bf16 v[48:63], v[84:87], v[92:95], v[48:63]
	global_load_lds_dwordx4 v124, s[12:13]
	s_add_i32 m0, s19, 0xe100
	s_waitcnt lgkmcnt(5)
	v_mfma_f32_32x32x16_bf16 v[32:47], v[84:87], v[96:99], v[32:47]
	global_load_lds_dwordx4 v125, s[12:13]
	s_waitcnt lgkmcnt(4)
	v_mfma_f32_32x32x16_bf16 v[16:31], v[88:91], v[92:95], v[16:31]
	v_mfma_f32_32x32x16_bf16 v[0:15], v[88:91], v[96:99], v[0:15]
	s_setprio 0
	ds_read_b128 v[84:87], v234
	ds_read_b128 v[92:95], v238
	ds_read_b128 v[96:99], v238 offset:4096
	ds_read_b128 v[88:91], v234 offset:4096
	s_setprio 1
	s_add_i32 m0, s19, 0x10100
	s_waitcnt lgkmcnt(6)
	v_mfma_f32_32x32x16_bf16 v[48:63], v[102:105], v[110:113], v[48:63]
	global_load_lds_dwordx4 v124, s[14:15]
	s_add_i32 m0, s19, 0x12100
	s_waitcnt lgkmcnt(5)
	v_mfma_f32_32x32x16_bf16 v[32:47], v[102:105], v[114:117], v[32:47]
	global_load_lds_dwordx4 v125, s[14:15]
	s_waitcnt lgkmcnt(4)
	v_mfma_f32_32x32x16_bf16 v[16:31], v[106:109], v[110:113], v[16:31]
	v_mfma_f32_32x32x16_bf16 v[0:15], v[106:109], v[114:117], v[0:15]
	s_setprio 0
	ds_read_b128 v[102:105], v235
	ds_read_b128 v[110:113], v239
	ds_read_b128 v[114:117], v239 offset:4096
	ds_read_b128 v[106:109], v235 offset:4096
	s_setprio 1
	s_add_i32 m0, s19, 0x14100
	s_waitcnt lgkmcnt(6)
	v_mfma_f32_32x32x16_bf16 v[48:63], v[84:87], v[92:95], v[48:63]
	global_load_lds_dwordx4 v126, s[14:15]
	s_add_i32 m0, s19, 0x16100
	s_waitcnt lgkmcnt(5)
	v_mfma_f32_32x32x16_bf16 v[32:47], v[84:87], v[96:99], v[32:47]
	global_load_lds_dwordx4 v127, s[14:15]
	s_waitcnt lgkmcnt(4)
	v_mfma_f32_32x32x16_bf16 v[16:31], v[88:91], v[92:95], v[16:31]
	v_mfma_f32_32x32x16_bf16 v[0:15], v[88:91], v[96:99], v[0:15]
	s_setprio 0
	s_add_u32 s12, s12, 0x80
	s_addc_u32 s13, s13, 0
	s_add_u32 s14, s14, 0x80
	s_addc_u32 s15, s15, 0
	s_waitcnt lgkmcnt(0)
	s_waitcnt vmcnt(6)
	s_barrier
	ds_read_b128 v[84:87], v224
	ds_read_b128 v[92:95], v228
	ds_read_b128 v[96:99], v228 offset:4096
	ds_read_b128 v[88:91], v224 offset:4096
	s_setprio 1
	v_mfma_f32_32x32x16_bf16 v[48:63], v[102:105], v[110:113], v[48:63]
	v_mfma_f32_32x32x16_bf16 v[32:47], v[102:105], v[114:117], v[32:47]
	v_mfma_f32_32x32x16_bf16 v[16:31], v[106:109], v[110:113], v[16:31]
	v_mfma_f32_32x32x16_bf16 v[0:15], v[106:109], v[114:117], v[0:15]
	s_setprio 0
	ds_read_b128 v[102:105], v225
	ds_read_b128 v[110:113], v229
	ds_read_b128 v[114:117], v229 offset:4096
	ds_read_b128 v[106:109], v225 offset:4096
	s_setprio 1
	s_add_i32 m0, s19, 0x1b900
	s_waitcnt lgkmcnt(6)
	v_mfma_f32_32x32x16_bf16 v[48:63], v[84:87], v[92:95], v[48:63]
	global_load_lds_dwordx4 v124, s[12:13]
	s_add_i32 m0, s19, 0x1d900
	s_waitcnt lgkmcnt(5)
	v_mfma_f32_32x32x16_bf16 v[32:47], v[84:87], v[96:99], v[32:47]
	global_load_lds_dwordx4 v125, s[12:13]
	s_waitcnt lgkmcnt(4)
	v_mfma_f32_32x32x16_bf16 v[16:31], v[88:91], v[92:95], v[16:31]
	v_mfma_f32_32x32x16_bf16 v[0:15], v[88:91], v[96:99], v[0:15]
	s_setprio 0
	ds_read_b128 v[84:87], v226
	ds_read_b128 v[92:95], v230
	ds_read_b128 v[96:99], v230 offset:4096
	ds_read_b128 v[88:91], v226 offset:4096
	s_setprio 1
	s_add_i32 m0, s19, 0x1f900
	s_waitcnt lgkmcnt(6)
	v_mfma_f32_32x32x16_bf16 v[48:63], v[102:105], v[110:113], v[48:63]
	global_load_lds_dwordx4 v124, s[14:15]
	s_add_i32 m0, s19, 0x21900
	s_waitcnt lgkmcnt(5)
	v_mfma_f32_32x32x16_bf16 v[32:47], v[102:105], v[114:117], v[32:47]
	global_load_lds_dwordx4 v125, s[14:15]
	s_waitcnt lgkmcnt(4)
	v_mfma_f32_32x32x16_bf16 v[16:31], v[106:109], v[110:113], v[16:31]
	v_mfma_f32_32x32x16_bf16 v[0:15], v[106:109], v[114:117], v[0:15]
	s_setprio 0
	ds_read_b128 v[102:105], v227
	ds_read_b128 v[110:113], v231
	ds_read_b128 v[114:117], v231 offset:4096
	ds_read_b128 v[106:109], v227 offset:4096
	s_setprio 1
	s_add_i32 m0, s19, 0x23900
	s_waitcnt lgkmcnt(6)
	v_mfma_f32_32x32x16_bf16 v[48:63], v[84:87], v[92:95], v[48:63]
	global_load_lds_dwordx4 v126, s[14:15]
	s_add_i32 m0, s19, 0x25900
	s_waitcnt lgkmcnt(5)
	v_mfma_f32_32x32x16_bf16 v[32:47], v[84:87], v[96:99], v[32:47]
	global_load_lds_dwordx4 v127, s[14:15]
	s_waitcnt lgkmcnt(4)
	v_mfma_f32_32x32x16_bf16 v[16:31], v[88:91], v[92:95], v[16:31]
	v_mfma_f32_32x32x16_bf16 v[0:15], v[88:91], v[96:99], v[0:15]
	s_setprio 0
	s_add_u32 s12, s12, 0x80
	s_addc_u32 s13, s13, 0
	s_add_u32 s14, s14, 0x80
	s_addc_u32 s15, s15, 0
	s_waitcnt lgkmcnt(0)
	s_waitcnt vmcnt(6)
	s_barrier
	ds_read_b128 v[84:87], v224 offset:49152
	ds_read_b128 v[92:95], v228 offset:49152
	ds_read_b128 v[96:99], v228 offset:53248
	ds_read_b128 v[88:91], v224 offset:53248
	s_setprio 1
	v_mfma_f32_32x32x16_bf16 v[48:63], v[102:105], v[110:113], v[48:63]
	v_mfma_f32_32x32x16_bf16 v[32:47], v[102:105], v[114:117], v[32:47]
	v_mfma_f32_32x32x16_bf16 v[16:31], v[106:109], v[110:113], v[16:31]
	v_mfma_f32_32x32x16_bf16 v[0:15], v[106:109], v[114:117], v[0:15]
	s_setprio 0
	ds_read_b128 v[102:105], v225 offset:49152
	ds_read_b128 v[110:113], v229 offset:49152
	ds_read_b128 v[114:117], v229 offset:53248
	ds_read_b128 v[106:109], v225 offset:53248
	s_setprio 1
	s_add_i32 m0, s19, 0x100
	s_waitcnt lgkmcnt(6)
	v_mfma_f32_32x32x16_bf16 v[48:63], v[84:87], v[92:95], v[48:63]
	global_load_lds_dwordx4 v124, s[12:13]
	s_add_i32 m0, s19, 0x2100
	s_waitcnt lgkmcnt(5)
	v_mfma_f32_32x32x16_bf16 v[32:47], v[84:87], v[96:99], v[32:47]
	global_load_lds_dwordx4 v125, s[12:13]
	s_waitcnt lgkmcnt(4)
	v_mfma_f32_32x32x16_bf16 v[16:31], v[88:91], v[92:95], v[16:31]
	v_mfma_f32_32x32x16_bf16 v[0:15], v[88:91], v[96:99], v[0:15]
	s_setprio 0
	ds_read_b128 v[84:87], v226 offset:49152
	ds_read_b128 v[92:95], v230 offset:49152
	ds_read_b128 v[96:99], v230 offset:53248
	ds_read_b128 v[88:91], v226 offset:53248
	s_setprio 1
	s_add_i32 m0, s19, 0x4100
	s_waitcnt lgkmcnt(6)
	v_mfma_f32_32x32x16_bf16 v[48:63], v[102:105], v[110:113], v[48:63]
	global_load_lds_dwordx4 v124, s[14:15]
	s_add_i32 m0, s19, 0x6100
	s_waitcnt lgkmcnt(5)
	v_mfma_f32_32x32x16_bf16 v[32:47], v[102:105], v[114:117], v[32:47]
	global_load_lds_dwordx4 v125, s[14:15]
	s_waitcnt lgkmcnt(4)
	v_mfma_f32_32x32x16_bf16 v[16:31], v[106:109], v[110:113], v[16:31]
	v_mfma_f32_32x32x16_bf16 v[0:15], v[106:109], v[114:117], v[0:15]
	s_setprio 0
	ds_read_b128 v[102:105], v227 offset:49152
	ds_read_b128 v[110:113], v231 offset:49152
	ds_read_b128 v[114:117], v231 offset:53248
	ds_read_b128 v[106:109], v227 offset:53248
	s_setprio 1
	s_add_i32 m0, s19, 0x8100
	s_waitcnt lgkmcnt(6)
	v_mfma_f32_32x32x16_bf16 v[48:63], v[84:87], v[92:95], v[48:63]
	global_load_lds_dwordx4 v126, s[14:15]
	s_add_i32 m0, s19, 0xa100
	s_waitcnt lgkmcnt(5)
	v_mfma_f32_32x32x16_bf16 v[32:47], v[84:87], v[96:99], v[32:47]
	global_load_lds_dwordx4 v127, s[14:15]
	s_waitcnt lgkmcnt(4)
	v_mfma_f32_32x32x16_bf16 v[16:31], v[88:91], v[92:95], v[16:31]
	v_mfma_f32_32x32x16_bf16 v[0:15], v[88:91], v[96:99], v[0:15]
	s_setprio 0
	s_add_u32 s12, s12, 0x80
	s_addc_u32 s13, s13, 0
	s_add_u32 s14, s14, 0x80
	s_addc_u32 s15, s15, 0
	s_waitcnt lgkmcnt(0)
	s_waitcnt vmcnt(6)
	s_barrier
	ds_read_b128 v[84:87], v232
	ds_read_b128 v[92:95], v236
	ds_read_b128 v[96:99], v236 offset:4096
	ds_read_b128 v[88:91], v232 offset:4096
	s_setprio 1
	v_mfma_f32_32x32x16_bf16 v[48:63], v[102:105], v[110:113], v[48:63]
	v_mfma_f32_32x32x16_bf16 v[32:47], v[102:105], v[114:117], v[32:47]
	v_mfma_f32_32x32x16_bf16 v[16:31], v[106:109], v[110:113], v[16:31]
	v_mfma_f32_32x32x16_bf16 v[0:15], v[106:109], v[114:117], v[0:15]
	s_setprio 0
	ds_read_b128 v[102:105], v233
	ds_read_b128 v[110:113], v237
	ds_read_b128 v[114:117], v237 offset:4096
	ds_read_b128 v[106:109], v233 offset:4096
	s_setprio 1
	s_add_i32 m0, s19, 0xc100
	s_waitcnt lgkmcnt(6)
	v_mfma_f32_32x32x16_bf16 v[48:63], v[84:87], v[92:95], v[48:63]
	global_load_lds_dwordx4 v124, s[12:13]
	s_add_i32 m0, s19, 0xe100
	s_waitcnt lgkmcnt(5)
	v_mfma_f32_32x32x16_bf16 v[32:47], v[84:87], v[96:99], v[32:47]
	global_load_lds_dwordx4 v125, s[12:13]
	s_waitcnt lgkmcnt(4)
	v_mfma_f32_32x32x16_bf16 v[16:31], v[88:91], v[92:95], v[16:31]
	v_mfma_f32_32x32x16_bf16 v[0:15], v[88:91], v[96:99], v[0:15]
	s_setprio 0
	ds_read_b128 v[84:87], v234
	ds_read_b128 v[92:95], v238
	ds_read_b128 v[96:99], v238 offset:4096
	ds_read_b128 v[88:91], v234 offset:4096
	s_setprio 1
	s_add_i32 m0, s19, 0x10100
	s_waitcnt lgkmcnt(6)
	v_mfma_f32_32x32x16_bf16 v[48:63], v[102:105], v[110:113], v[48:63]
	global_load_lds_dwordx4 v124, s[14:15]
	s_add_i32 m0, s19, 0x12100
	s_waitcnt lgkmcnt(5)
	v_mfma_f32_32x32x16_bf16 v[32:47], v[102:105], v[114:117], v[32:47]
	global_load_lds_dwordx4 v125, s[14:15]
	s_waitcnt lgkmcnt(4)
	v_mfma_f32_32x32x16_bf16 v[16:31], v[106:109], v[110:113], v[16:31]
	v_mfma_f32_32x32x16_bf16 v[0:15], v[106:109], v[114:117], v[0:15]
	s_setprio 0
	ds_read_b128 v[102:105], v235
	ds_read_b128 v[110:113], v239
	ds_read_b128 v[114:117], v239 offset:4096
	ds_read_b128 v[106:109], v235 offset:4096
	s_setprio 1
	s_add_i32 m0, s19, 0x14100
	s_waitcnt lgkmcnt(6)
	v_mfma_f32_32x32x16_bf16 v[48:63], v[84:87], v[92:95], v[48:63]
	global_load_lds_dwordx4 v126, s[14:15]
	s_add_i32 m0, s19, 0x16100
	s_waitcnt lgkmcnt(5)
	v_mfma_f32_32x32x16_bf16 v[32:47], v[84:87], v[96:99], v[32:47]
	global_load_lds_dwordx4 v127, s[14:15]
	s_waitcnt lgkmcnt(4)
	v_mfma_f32_32x32x16_bf16 v[16:31], v[88:91], v[92:95], v[16:31]
	v_mfma_f32_32x32x16_bf16 v[0:15], v[88:91], v[96:99], v[0:15]
	s_setprio 0
	s_add_u32 s12, s12, 0x80
	s_addc_u32 s13, s13, 0
	s_add_u32 s14, s14, 0x80
	s_addc_u32 s15, s15, 0
	s_waitcnt lgkmcnt(0)
	s_waitcnt vmcnt(6)
	s_barrier
	ds_read_b128 v[84:87], v224
	ds_read_b128 v[92:95], v228
	ds_read_b128 v[96:99], v228 offset:4096
	ds_read_b128 v[88:91], v224 offset:4096
	s_setprio 1
	v_mfma_f32_32x32x16_bf16 v[48:63], v[102:105], v[110:113], v[48:63]
	v_mfma_f32_32x32x16_bf16 v[32:47], v[102:105], v[114:117], v[32:47]
	v_mfma_f32_32x32x16_bf16 v[16:31], v[106:109], v[110:113], v[16:31]
	v_mfma_f32_32x32x16_bf16 v[0:15], v[106:109], v[114:117], v[0:15]
	s_setprio 0
	ds_read_b128 v[102:105], v225
	ds_read_b128 v[110:113], v229
	ds_read_b128 v[114:117], v229 offset:4096
	ds_read_b128 v[106:109], v225 offset:4096
	s_setprio 1
	s_add_i32 m0, s19, 0x1b900
	s_waitcnt lgkmcnt(6)
	v_mfma_f32_32x32x16_bf16 v[48:63], v[84:87], v[92:95], v[48:63]
	global_load_lds_dwordx4 v124, s[12:13]
	s_add_i32 m0, s19, 0x1d900
	s_waitcnt lgkmcnt(5)
	v_mfma_f32_32x32x16_bf16 v[32:47], v[84:87], v[96:99], v[32:47]
	global_load_lds_dwordx4 v125, s[12:13]
	s_waitcnt lgkmcnt(4)
	v_mfma_f32_32x32x16_bf16 v[16:31], v[88:91], v[92:95], v[16:31]
	v_mfma_f32_32x32x16_bf16 v[0:15], v[88:91], v[96:99], v[0:15]
	s_setprio 0
	ds_read_b128 v[84:87], v226
	ds_read_b128 v[92:95], v230
	ds_read_b128 v[96:99], v230 offset:4096
	ds_read_b128 v[88:91], v226 offset:4096
	s_setprio 1
	s_add_i32 m0, s19, 0x1f900
	s_waitcnt lgkmcnt(6)
	v_mfma_f32_32x32x16_bf16 v[48:63], v[102:105], v[110:113], v[48:63]
	global_load_lds_dwordx4 v124, s[14:15]
	s_add_i32 m0, s19, 0x21900
	s_waitcnt lgkmcnt(5)
	v_mfma_f32_32x32x16_bf16 v[32:47], v[102:105], v[114:117], v[32:47]
	global_load_lds_dwordx4 v125, s[14:15]
	s_waitcnt lgkmcnt(4)
	v_mfma_f32_32x32x16_bf16 v[16:31], v[106:109], v[110:113], v[16:31]
	v_mfma_f32_32x32x16_bf16 v[0:15], v[106:109], v[114:117], v[0:15]
	s_setprio 0
	ds_read_b128 v[102:105], v227
	ds_read_b128 v[110:113], v231
	ds_read_b128 v[114:117], v231 offset:4096
	ds_read_b128 v[106:109], v227 offset:4096
	s_setprio 1
	s_add_i32 m0, s19, 0x23900
	s_waitcnt lgkmcnt(6)
	v_mfma_f32_32x32x16_bf16 v[48:63], v[84:87], v[92:95], v[48:63]
	global_load_lds_dwordx4 v126, s[14:15]
	s_add_i32 m0, s19, 0x25900
	s_waitcnt lgkmcnt(5)
	v_mfma_f32_32x32x16_bf16 v[32:47], v[84:87], v[96:99], v[32:47]
	global_load_lds_dwordx4 v127, s[14:15]
	s_waitcnt lgkmcnt(4)
	v_mfma_f32_32x32x16_bf16 v[16:31], v[88:91], v[92:95], v[16:31]
	v_mfma_f32_32x32x16_bf16 v[0:15], v[88:91], v[96:99], v[0:15]
	s_setprio 0
	s_add_u32 s12, s12, 0x80
	s_addc_u32 s13, s13, 0
	s_add_u32 s14, s14, 0x80
	s_addc_u32 s15, s15, 0
	s_waitcnt lgkmcnt(0)
	s_waitcnt vmcnt(6)
	s_barrier
	ds_read_b128 v[84:87], v224 offset:49152
	ds_read_b128 v[92:95], v228 offset:49152
	ds_read_b128 v[96:99], v228 offset:53248
	ds_read_b128 v[88:91], v224 offset:53248
	s_setprio 1
	v_mfma_f32_32x32x16_bf16 v[48:63], v[102:105], v[110:113], v[48:63]
	v_mfma_f32_32x32x16_bf16 v[32:47], v[102:105], v[114:117], v[32:47]
	v_mfma_f32_32x32x16_bf16 v[16:31], v[106:109], v[110:113], v[16:31]
	v_mfma_f32_32x32x16_bf16 v[0:15], v[106:109], v[114:117], v[0:15]
	s_setprio 0
	ds_read_b128 v[102:105], v225 offset:49152
	ds_read_b128 v[110:113], v229 offset:49152
	ds_read_b128 v[114:117], v229 offset:53248
	ds_read_b128 v[106:109], v225 offset:53248
	s_setprio 1
	s_add_i32 m0, s19, 0x100
	s_waitcnt lgkmcnt(6)
	v_mfma_f32_32x32x16_bf16 v[48:63], v[84:87], v[92:95], v[48:63]
	global_load_lds_dwordx4 v124, s[12:13]
	s_add_i32 m0, s19, 0x2100
	s_waitcnt lgkmcnt(5)
	v_mfma_f32_32x32x16_bf16 v[32:47], v[84:87], v[96:99], v[32:47]
	global_load_lds_dwordx4 v125, s[12:13]
	s_waitcnt lgkmcnt(4)
	v_mfma_f32_32x32x16_bf16 v[16:31], v[88:91], v[92:95], v[16:31]
	v_mfma_f32_32x32x16_bf16 v[0:15], v[88:91], v[96:99], v[0:15]
	s_setprio 0
	ds_read_b128 v[84:87], v226 offset:49152
	ds_read_b128 v[92:95], v230 offset:49152
	ds_read_b128 v[96:99], v230 offset:53248
	ds_read_b128 v[88:91], v226 offset:53248
	s_setprio 1
	s_add_i32 m0, s19, 0x4100
	s_waitcnt lgkmcnt(6)
	v_mfma_f32_32x32x16_bf16 v[48:63], v[102:105], v[110:113], v[48:63]
	global_load_lds_dwordx4 v124, s[14:15]
	s_add_i32 m0, s19, 0x6100
	s_waitcnt lgkmcnt(5)
	v_mfma_f32_32x32x16_bf16 v[32:47], v[102:105], v[114:117], v[32:47]
	global_load_lds_dwordx4 v125, s[14:15]
	s_waitcnt lgkmcnt(4)
	v_mfma_f32_32x32x16_bf16 v[16:31], v[106:109], v[110:113], v[16:31]
	v_mfma_f32_32x32x16_bf16 v[0:15], v[106:109], v[114:117], v[0:15]
	s_setprio 0
	ds_read_b128 v[102:105], v227 offset:49152
	ds_read_b128 v[110:113], v231 offset:49152
	ds_read_b128 v[114:117], v231 offset:53248
	ds_read_b128 v[106:109], v227 offset:53248
	s_setprio 1
	s_add_i32 m0, s19, 0x8100
	s_waitcnt lgkmcnt(6)
	v_mfma_f32_32x32x16_bf16 v[48:63], v[84:87], v[92:95], v[48:63]
	global_load_lds_dwordx4 v126, s[14:15]
	s_add_i32 m0, s19, 0xa100
	s_waitcnt lgkmcnt(5)
	v_mfma_f32_32x32x16_bf16 v[32:47], v[84:87], v[96:99], v[32:47]
	global_load_lds_dwordx4 v127, s[14:15]
	s_waitcnt lgkmcnt(4)
	v_mfma_f32_32x32x16_bf16 v[16:31], v[88:91], v[92:95], v[16:31]
	v_mfma_f32_32x32x16_bf16 v[0:15], v[88:91], v[96:99], v[0:15]
	s_setprio 0
	s_add_u32 s12, s12, 0x80
	s_addc_u32 s13, s13, 0
	s_add_u32 s14, s14, 0x80
	s_addc_u32 s15, s15, 0
	s_waitcnt lgkmcnt(0)
	s_waitcnt vmcnt(6)
	s_barrier
	ds_read_b128 v[84:87], v232
	ds_read_b128 v[92:95], v236
	ds_read_b128 v[96:99], v236 offset:4096
	ds_read_b128 v[88:91], v232 offset:4096
	s_setprio 1
	v_mfma_f32_32x32x16_bf16 v[48:63], v[102:105], v[110:113], v[48:63]
	v_mfma_f32_32x32x16_bf16 v[32:47], v[102:105], v[114:117], v[32:47]
	v_mfma_f32_32x32x16_bf16 v[16:31], v[106:109], v[110:113], v[16:31]
	v_mfma_f32_32x32x16_bf16 v[0:15], v[106:109], v[114:117], v[0:15]
	s_setprio 0
	ds_read_b128 v[102:105], v233
	ds_read_b128 v[110:113], v237
	ds_read_b128 v[114:117], v237 offset:4096
	ds_read_b128 v[106:109], v233 offset:4096
	s_setprio 1
	s_add_i32 m0, s19, 0xc100
	s_waitcnt lgkmcnt(6)
	v_mfma_f32_32x32x16_bf16 v[48:63], v[84:87], v[92:95], v[48:63]
	global_load_lds_dwordx4 v124, s[12:13]
	s_add_i32 m0, s19, 0xe100
	s_waitcnt lgkmcnt(5)
	v_mfma_f32_32x32x16_bf16 v[32:47], v[84:87], v[96:99], v[32:47]
	global_load_lds_dwordx4 v125, s[12:13]
	s_waitcnt lgkmcnt(4)
	v_mfma_f32_32x32x16_bf16 v[16:31], v[88:91], v[92:95], v[16:31]
	v_mfma_f32_32x32x16_bf16 v[0:15], v[88:91], v[96:99], v[0:15]
	s_setprio 0
	ds_read_b128 v[84:87], v234
	ds_read_b128 v[92:95], v238
	ds_read_b128 v[96:99], v238 offset:4096
	ds_read_b128 v[88:91], v234 offset:4096
	s_setprio 1
	s_add_i32 m0, s19, 0x10100
	s_waitcnt lgkmcnt(6)
	v_mfma_f32_32x32x16_bf16 v[48:63], v[102:105], v[110:113], v[48:63]
	global_load_lds_dwordx4 v124, s[14:15]
	s_add_i32 m0, s19, 0x12100
	s_waitcnt lgkmcnt(5)
	v_mfma_f32_32x32x16_bf16 v[32:47], v[102:105], v[114:117], v[32:47]
	global_load_lds_dwordx4 v125, s[14:15]
	s_waitcnt lgkmcnt(4)
	v_mfma_f32_32x32x16_bf16 v[16:31], v[106:109], v[110:113], v[16:31]
	v_mfma_f32_32x32x16_bf16 v[0:15], v[106:109], v[114:117], v[0:15]
	s_setprio 0
	ds_read_b128 v[102:105], v235
	ds_read_b128 v[110:113], v239
	ds_read_b128 v[114:117], v239 offset:4096
	ds_read_b128 v[106:109], v235 offset:4096
	s_setprio 1
	s_add_i32 m0, s19, 0x14100
	s_waitcnt lgkmcnt(6)
	v_mfma_f32_32x32x16_bf16 v[48:63], v[84:87], v[92:95], v[48:63]
	global_load_lds_dwordx4 v126, s[14:15]
	s_add_i32 m0, s19, 0x16100
	s_waitcnt lgkmcnt(5)
	v_mfma_f32_32x32x16_bf16 v[32:47], v[84:87], v[96:99], v[32:47]
	global_load_lds_dwordx4 v127, s[14:15]
	s_waitcnt lgkmcnt(4)
	v_mfma_f32_32x32x16_bf16 v[16:31], v[88:91], v[92:95], v[16:31]
	v_mfma_f32_32x32x16_bf16 v[0:15], v[88:91], v[96:99], v[0:15]
	s_setprio 0
	s_add_u32 s12, s12, 0x80
	s_addc_u32 s13, s13, 0
	s_add_u32 s14, s14, 0x80
	s_addc_u32 s15, s15, 0
	s_waitcnt lgkmcnt(0)
	s_waitcnt vmcnt(6)
	s_barrier
	ds_read_b128 v[84:87], v224
	ds_read_b128 v[92:95], v228
	ds_read_b128 v[96:99], v228 offset:4096
	ds_read_b128 v[88:91], v224 offset:4096
	s_setprio 1
	v_mfma_f32_32x32x16_bf16 v[48:63], v[102:105], v[110:113], v[48:63]
	v_mfma_f32_32x32x16_bf16 v[32:47], v[102:105], v[114:117], v[32:47]
	v_mfma_f32_32x32x16_bf16 v[16:31], v[106:109], v[110:113], v[16:31]
	v_mfma_f32_32x32x16_bf16 v[0:15], v[106:109], v[114:117], v[0:15]
	s_setprio 0
	ds_read_b128 v[102:105], v225
	ds_read_b128 v[110:113], v229
	ds_read_b128 v[114:117], v229 offset:4096
	ds_read_b128 v[106:109], v225 offset:4096
	s_setprio 1
	s_add_i32 m0, s19, 0x1b900
	s_waitcnt lgkmcnt(6)
	v_mfma_f32_32x32x16_bf16 v[48:63], v[84:87], v[92:95], v[48:63]
	global_load_lds_dwordx4 v124, s[12:13]
	s_add_i32 m0, s19, 0x1d900
	s_waitcnt lgkmcnt(5)
	v_mfma_f32_32x32x16_bf16 v[32:47], v[84:87], v[96:99], v[32:47]
	global_load_lds_dwordx4 v125, s[12:13]
	s_waitcnt lgkmcnt(4)
	v_mfma_f32_32x32x16_bf16 v[16:31], v[88:91], v[92:95], v[16:31]
	v_mfma_f32_32x32x16_bf16 v[0:15], v[88:91], v[96:99], v[0:15]
	s_setprio 0
	ds_read_b128 v[84:87], v226
	ds_read_b128 v[92:95], v230
	ds_read_b128 v[96:99], v230 offset:4096
	ds_read_b128 v[88:91], v226 offset:4096
	s_setprio 1
	s_add_i32 m0, s19, 0x1f900
	s_waitcnt lgkmcnt(6)
	v_mfma_f32_32x32x16_bf16 v[48:63], v[102:105], v[110:113], v[48:63]
	global_load_lds_dwordx4 v124, s[14:15]
	s_add_i32 m0, s19, 0x21900
	s_waitcnt lgkmcnt(5)
	v_mfma_f32_32x32x16_bf16 v[32:47], v[102:105], v[114:117], v[32:47]
	global_load_lds_dwordx4 v125, s[14:15]
	s_waitcnt lgkmcnt(4)
	v_mfma_f32_32x32x16_bf16 v[16:31], v[106:109], v[110:113], v[16:31]
	v_mfma_f32_32x32x16_bf16 v[0:15], v[106:109], v[114:117], v[0:15]
	s_setprio 0
	ds_read_b128 v[102:105], v227
	ds_read_b128 v[110:113], v231
	ds_read_b128 v[114:117], v231 offset:4096
	ds_read_b128 v[106:109], v227 offset:4096
	s_setprio 1
	s_add_i32 m0, s19, 0x23900
	s_waitcnt lgkmcnt(6)
	v_mfma_f32_32x32x16_bf16 v[48:63], v[84:87], v[92:95], v[48:63]
	global_load_lds_dwordx4 v126, s[14:15]
	s_add_i32 m0, s19, 0x25900
	s_waitcnt lgkmcnt(5)
	v_mfma_f32_32x32x16_bf16 v[32:47], v[84:87], v[96:99], v[32:47]
	global_load_lds_dwordx4 v127, s[14:15]
	s_waitcnt lgkmcnt(4)
	v_mfma_f32_32x32x16_bf16 v[16:31], v[88:91], v[92:95], v[16:31]
	v_mfma_f32_32x32x16_bf16 v[0:15], v[88:91], v[96:99], v[0:15]
	s_setprio 0
	s_add_u32 s12, s12, 0x80
	s_addc_u32 s13, s13, 0
	s_add_u32 s14, s14, 0x80
	s_addc_u32 s15, s15, 0
	s_waitcnt lgkmcnt(0)
	s_waitcnt vmcnt(6)
	s_barrier
	ds_read_b128 v[84:87], v224 offset:49152
	ds_read_b128 v[92:95], v228 offset:49152
	ds_read_b128 v[96:99], v228 offset:53248
	ds_read_b128 v[88:91], v224 offset:53248
	s_setprio 1
	v_mfma_f32_32x32x16_bf16 v[48:63], v[102:105], v[110:113], v[48:63]
	v_mfma_f32_32x32x16_bf16 v[32:47], v[102:105], v[114:117], v[32:47]
	v_mfma_f32_32x32x16_bf16 v[16:31], v[106:109], v[110:113], v[16:31]
	v_mfma_f32_32x32x16_bf16 v[0:15], v[106:109], v[114:117], v[0:15]
	s_setprio 0
	ds_read_b128 v[102:105], v225 offset:49152
	ds_read_b128 v[110:113], v229 offset:49152
	ds_read_b128 v[114:117], v229 offset:53248
	ds_read_b128 v[106:109], v225 offset:53248
	s_setprio 1
	s_add_i32 m0, s19, 0x100
	s_waitcnt lgkmcnt(6)
	v_mfma_f32_32x32x16_bf16 v[48:63], v[84:87], v[92:95], v[48:63]
	global_load_lds_dwordx4 v124, s[12:13]
	s_add_i32 m0, s19, 0x2100
	s_waitcnt lgkmcnt(5)
	v_mfma_f32_32x32x16_bf16 v[32:47], v[84:87], v[96:99], v[32:47]
	global_load_lds_dwordx4 v125, s[12:13]
	s_waitcnt lgkmcnt(4)
	v_mfma_f32_32x32x16_bf16 v[16:31], v[88:91], v[92:95], v[16:31]
	v_mfma_f32_32x32x16_bf16 v[0:15], v[88:91], v[96:99], v[0:15]
	s_setprio 0
	ds_read_b128 v[84:87], v226 offset:49152
	ds_read_b128 v[92:95], v230 offset:49152
	ds_read_b128 v[96:99], v230 offset:53248
	ds_read_b128 v[88:91], v226 offset:53248
	s_setprio 1
	s_add_i32 m0, s19, 0x4100
	s_waitcnt lgkmcnt(6)
	v_mfma_f32_32x32x16_bf16 v[48:63], v[102:105], v[110:113], v[48:63]
	global_load_lds_dwordx4 v124, s[14:15]
	s_add_i32 m0, s19, 0x6100
	s_waitcnt lgkmcnt(5)
	v_mfma_f32_32x32x16_bf16 v[32:47], v[102:105], v[114:117], v[32:47]
	global_load_lds_dwordx4 v125, s[14:15]
	s_waitcnt lgkmcnt(4)
	v_mfma_f32_32x32x16_bf16 v[16:31], v[106:109], v[110:113], v[16:31]
	v_mfma_f32_32x32x16_bf16 v[0:15], v[106:109], v[114:117], v[0:15]
	s_setprio 0
	ds_read_b128 v[102:105], v227 offset:49152
	ds_read_b128 v[110:113], v231 offset:49152
	ds_read_b128 v[114:117], v231 offset:53248
	ds_read_b128 v[106:109], v227 offset:53248
	s_setprio 1
	s_add_i32 m0, s19, 0x8100
	s_waitcnt lgkmcnt(6)
	v_mfma_f32_32x32x16_bf16 v[48:63], v[84:87], v[92:95], v[48:63]
	global_load_lds_dwordx4 v126, s[14:15]
	s_add_i32 m0, s19, 0xa100
	s_waitcnt lgkmcnt(5)
	v_mfma_f32_32x32x16_bf16 v[32:47], v[84:87], v[96:99], v[32:47]
	global_load_lds_dwordx4 v127, s[14:15]
	s_waitcnt lgkmcnt(4)
	v_mfma_f32_32x32x16_bf16 v[16:31], v[88:91], v[92:95], v[16:31]
	v_mfma_f32_32x32x16_bf16 v[0:15], v[88:91], v[96:99], v[0:15]
	s_setprio 0
	s_add_u32 s12, s12, 0x80
	s_addc_u32 s13, s13, 0
	s_add_u32 s14, s14, 0x80
	s_addc_u32 s15, s15, 0
	s_waitcnt lgkmcnt(0)
	s_waitcnt vmcnt(6)
	s_barrier
	ds_read_b128 v[84:87], v232
	ds_read_b128 v[92:95], v236
	ds_read_b128 v[96:99], v236 offset:4096
	ds_read_b128 v[88:91], v232 offset:4096
	s_setprio 1
	v_mfma_f32_32x32x16_bf16 v[48:63], v[102:105], v[110:113], v[48:63]
	v_mfma_f32_32x32x16_bf16 v[32:47], v[102:105], v[114:117], v[32:47]
	v_mfma_f32_32x32x16_bf16 v[16:31], v[106:109], v[110:113], v[16:31]
	v_mfma_f32_32x32x16_bf16 v[0:15], v[106:109], v[114:117], v[0:15]
	s_setprio 0
	ds_read_b128 v[102:105], v233
	ds_read_b128 v[110:113], v237
	ds_read_b128 v[114:117], v237 offset:4096
	ds_read_b128 v[106:109], v233 offset:4096
	s_setprio 1
	s_add_i32 m0, s19, 0xc100
	s_waitcnt lgkmcnt(6)
	v_mfma_f32_32x32x16_bf16 v[48:63], v[84:87], v[92:95], v[48:63]
	global_load_lds_dwordx4 v124, s[12:13]
	s_add_i32 m0, s19, 0xe100
	s_waitcnt lgkmcnt(5)
	v_mfma_f32_32x32x16_bf16 v[32:47], v[84:87], v[96:99], v[32:47]
	global_load_lds_dwordx4 v125, s[12:13]
	s_waitcnt lgkmcnt(4)
	v_mfma_f32_32x32x16_bf16 v[16:31], v[88:91], v[92:95], v[16:31]
	v_mfma_f32_32x32x16_bf16 v[0:15], v[88:91], v[96:99], v[0:15]
	s_setprio 0
	ds_read_b128 v[84:87], v234
	ds_read_b128 v[92:95], v238
	ds_read_b128 v[96:99], v238 offset:4096
	ds_read_b128 v[88:91], v234 offset:4096
	s_setprio 1
	s_add_i32 m0, s19, 0x10100
	s_waitcnt lgkmcnt(6)
	v_mfma_f32_32x32x16_bf16 v[48:63], v[102:105], v[110:113], v[48:63]
	global_load_lds_dwordx4 v124, s[14:15]
	s_add_i32 m0, s19, 0x12100
	s_waitcnt lgkmcnt(5)
	v_mfma_f32_32x32x16_bf16 v[32:47], v[102:105], v[114:117], v[32:47]
	global_load_lds_dwordx4 v125, s[14:15]
	s_waitcnt lgkmcnt(4)
	v_mfma_f32_32x32x16_bf16 v[16:31], v[106:109], v[110:113], v[16:31]
	v_mfma_f32_32x32x16_bf16 v[0:15], v[106:109], v[114:117], v[0:15]
	s_setprio 0
	ds_read_b128 v[102:105], v235
	ds_read_b128 v[110:113], v239
	ds_read_b128 v[114:117], v239 offset:4096
	ds_read_b128 v[106:109], v235 offset:4096
	s_setprio 1
	s_add_i32 m0, s19, 0x14100
	s_waitcnt lgkmcnt(6)
	v_mfma_f32_32x32x16_bf16 v[48:63], v[84:87], v[92:95], v[48:63]
	global_load_lds_dwordx4 v126, s[14:15]
	s_add_i32 m0, s19, 0x16100
	s_waitcnt lgkmcnt(5)
	v_mfma_f32_32x32x16_bf16 v[32:47], v[84:87], v[96:99], v[32:47]
	global_load_lds_dwordx4 v127, s[14:15]
	s_waitcnt lgkmcnt(4)
	v_mfma_f32_32x32x16_bf16 v[16:31], v[88:91], v[92:95], v[16:31]
	v_mfma_f32_32x32x16_bf16 v[0:15], v[88:91], v[96:99], v[0:15]
	s_setprio 0
	s_add_u32 s12, s12, 0x80
	s_addc_u32 s13, s13, 0
	s_add_u32 s14, s14, 0x80
	s_addc_u32 s15, s15, 0
	s_waitcnt lgkmcnt(0)
	s_waitcnt vmcnt(6)
	s_barrier
	ds_read_b128 v[84:87], v224
	ds_read_b128 v[92:95], v228
	ds_read_b128 v[96:99], v228 offset:4096
	ds_read_b128 v[88:91], v224 offset:4096
	s_setprio 1
	v_mfma_f32_32x32x16_bf16 v[48:63], v[102:105], v[110:113], v[48:63]
	v_mfma_f32_32x32x16_bf16 v[32:47], v[102:105], v[114:117], v[32:47]
	v_mfma_f32_32x32x16_bf16 v[16:31], v[106:109], v[110:113], v[16:31]
	v_mfma_f32_32x32x16_bf16 v[0:15], v[106:109], v[114:117], v[0:15]
	s_setprio 0
	ds_read_b128 v[102:105], v225
	ds_read_b128 v[110:113], v229
	ds_read_b128 v[114:117], v229 offset:4096
	ds_read_b128 v[106:109], v225 offset:4096
	s_setprio 1
	s_add_i32 m0, s19, 0x1b900
	s_waitcnt lgkmcnt(6)
	v_mfma_f32_32x32x16_bf16 v[48:63], v[84:87], v[92:95], v[48:63]
	global_load_lds_dwordx4 v124, s[12:13]
	s_add_i32 m0, s19, 0x1d900
	s_waitcnt lgkmcnt(5)
	v_mfma_f32_32x32x16_bf16 v[32:47], v[84:87], v[96:99], v[32:47]
	global_load_lds_dwordx4 v125, s[12:13]
	s_waitcnt lgkmcnt(4)
	v_mfma_f32_32x32x16_bf16 v[16:31], v[88:91], v[92:95], v[16:31]
	v_mfma_f32_32x32x16_bf16 v[0:15], v[88:91], v[96:99], v[0:15]
	s_setprio 0
	ds_read_b128 v[84:87], v226
	ds_read_b128 v[92:95], v230
	ds_read_b128 v[96:99], v230 offset:4096
	ds_read_b128 v[88:91], v226 offset:4096
	s_setprio 1
	s_add_i32 m0, s19, 0x1f900
	s_waitcnt lgkmcnt(6)
	v_mfma_f32_32x32x16_bf16 v[48:63], v[102:105], v[110:113], v[48:63]
	global_load_lds_dwordx4 v124, s[14:15]
	s_add_i32 m0, s19, 0x21900
	s_waitcnt lgkmcnt(5)
	v_mfma_f32_32x32x16_bf16 v[32:47], v[102:105], v[114:117], v[32:47]
	global_load_lds_dwordx4 v125, s[14:15]
	s_waitcnt lgkmcnt(4)
	v_mfma_f32_32x32x16_bf16 v[16:31], v[106:109], v[110:113], v[16:31]
	v_mfma_f32_32x32x16_bf16 v[0:15], v[106:109], v[114:117], v[0:15]
	s_setprio 0
	ds_read_b128 v[102:105], v227
	ds_read_b128 v[110:113], v231
	ds_read_b128 v[114:117], v231 offset:4096
	ds_read_b128 v[106:109], v227 offset:4096
	s_setprio 1
	s_add_i32 m0, s19, 0x23900
	s_waitcnt lgkmcnt(6)
	v_mfma_f32_32x32x16_bf16 v[48:63], v[84:87], v[92:95], v[48:63]
	global_load_lds_dwordx4 v126, s[14:15]
	s_add_i32 m0, s19, 0x25900
	s_waitcnt lgkmcnt(5)
	v_mfma_f32_32x32x16_bf16 v[32:47], v[84:87], v[96:99], v[32:47]
	global_load_lds_dwordx4 v127, s[14:15]
	s_waitcnt lgkmcnt(4)
	v_mfma_f32_32x32x16_bf16 v[16:31], v[88:91], v[92:95], v[16:31]
	v_mfma_f32_32x32x16_bf16 v[0:15], v[88:91], v[96:99], v[0:15]
	s_setprio 0
	s_add_u32 s12, s12, 0x80
	s_addc_u32 s13, s13, 0
	s_add_u32 s14, s14, 0x80
	s_addc_u32 s15, s15, 0
	s_waitcnt lgkmcnt(0)
	s_waitcnt vmcnt(6)
	s_barrier
	ds_read_b128 v[84:87], v224 offset:49152
	ds_read_b128 v[92:95], v228 offset:49152
	ds_read_b128 v[96:99], v228 offset:53248
	ds_read_b128 v[88:91], v224 offset:53248
	s_setprio 1
	v_mfma_f32_32x32x16_bf16 v[48:63], v[102:105], v[110:113], v[48:63]
	v_mfma_f32_32x32x16_bf16 v[32:47], v[102:105], v[114:117], v[32:47]
	v_mfma_f32_32x32x16_bf16 v[16:31], v[106:109], v[110:113], v[16:31]
	v_mfma_f32_32x32x16_bf16 v[0:15], v[106:109], v[114:117], v[0:15]
	s_setprio 0
	ds_read_b128 v[102:105], v225 offset:49152
	ds_read_b128 v[110:113], v229 offset:49152
	ds_read_b128 v[114:117], v229 offset:53248
	ds_read_b128 v[106:109], v225 offset:53248
	s_setprio 1
	s_add_i32 m0, s19, 0x100
	s_waitcnt lgkmcnt(6)
	v_mfma_f32_32x32x16_bf16 v[48:63], v[84:87], v[92:95], v[48:63]
	global_load_lds_dwordx4 v124, s[12:13]
	s_add_i32 m0, s19, 0x2100
	s_waitcnt lgkmcnt(5)
	v_mfma_f32_32x32x16_bf16 v[32:47], v[84:87], v[96:99], v[32:47]
	global_load_lds_dwordx4 v125, s[12:13]
	s_waitcnt lgkmcnt(4)
	v_mfma_f32_32x32x16_bf16 v[16:31], v[88:91], v[92:95], v[16:31]
	v_mfma_f32_32x32x16_bf16 v[0:15], v[88:91], v[96:99], v[0:15]
	s_setprio 0
	ds_read_b128 v[84:87], v226 offset:49152
	ds_read_b128 v[92:95], v230 offset:49152
	ds_read_b128 v[96:99], v230 offset:53248
	ds_read_b128 v[88:91], v226 offset:53248
	s_setprio 1
	s_add_i32 m0, s19, 0x4100
	s_waitcnt lgkmcnt(6)
	v_mfma_f32_32x32x16_bf16 v[48:63], v[102:105], v[110:113], v[48:63]
	global_load_lds_dwordx4 v124, s[14:15]
	s_add_i32 m0, s19, 0x6100
	s_waitcnt lgkmcnt(5)
	v_mfma_f32_32x32x16_bf16 v[32:47], v[102:105], v[114:117], v[32:47]
	global_load_lds_dwordx4 v125, s[14:15]
	s_waitcnt lgkmcnt(4)
	v_mfma_f32_32x32x16_bf16 v[16:31], v[106:109], v[110:113], v[16:31]
	v_mfma_f32_32x32x16_bf16 v[0:15], v[106:109], v[114:117], v[0:15]
	s_setprio 0
	ds_read_b128 v[102:105], v227 offset:49152
	ds_read_b128 v[110:113], v231 offset:49152
	ds_read_b128 v[114:117], v231 offset:53248
	ds_read_b128 v[106:109], v227 offset:53248
	s_setprio 1
	s_add_i32 m0, s19, 0x8100
	s_waitcnt lgkmcnt(6)
	v_mfma_f32_32x32x16_bf16 v[48:63], v[84:87], v[92:95], v[48:63]
	global_load_lds_dwordx4 v126, s[14:15]
	s_add_i32 m0, s19, 0xa100
	s_waitcnt lgkmcnt(5)
	v_mfma_f32_32x32x16_bf16 v[32:47], v[84:87], v[96:99], v[32:47]
	global_load_lds_dwordx4 v127, s[14:15]
	s_waitcnt lgkmcnt(4)
	v_mfma_f32_32x32x16_bf16 v[16:31], v[88:91], v[92:95], v[16:31]
	v_mfma_f32_32x32x16_bf16 v[0:15], v[88:91], v[96:99], v[0:15]
	s_setprio 0
	s_add_u32 s12, s12, 0x80
	s_addc_u32 s13, s13, 0
	s_add_u32 s14, s14, 0x80
	s_addc_u32 s15, s15, 0
	s_waitcnt lgkmcnt(0)
	s_waitcnt vmcnt(6)
	s_barrier
	ds_read_b128 v[84:87], v232
	ds_read_b128 v[92:95], v236
	ds_read_b128 v[96:99], v236 offset:4096
	ds_read_b128 v[88:91], v232 offset:4096
	s_setprio 1
	v_mfma_f32_32x32x16_bf16 v[48:63], v[102:105], v[110:113], v[48:63]
	v_mfma_f32_32x32x16_bf16 v[32:47], v[102:105], v[114:117], v[32:47]
	v_mfma_f32_32x32x16_bf16 v[16:31], v[106:109], v[110:113], v[16:31]
	v_mfma_f32_32x32x16_bf16 v[0:15], v[106:109], v[114:117], v[0:15]
	s_setprio 0
	ds_read_b128 v[102:105], v233
	ds_read_b128 v[110:113], v237
	ds_read_b128 v[114:117], v237 offset:4096
	ds_read_b128 v[106:109], v233 offset:4096
	s_setprio 1
	s_waitcnt lgkmcnt(6)
	v_mfma_f32_32x32x16_bf16 v[48:63], v[84:87], v[92:95], v[48:63]
	s_waitcnt lgkmcnt(5)
	v_mfma_f32_32x32x16_bf16 v[32:47], v[84:87], v[96:99], v[32:47]
	s_waitcnt lgkmcnt(4)
	v_mfma_f32_32x32x16_bf16 v[16:31], v[88:91], v[92:95], v[16:31]
	v_mfma_f32_32x32x16_bf16 v[0:15], v[88:91], v[96:99], v[0:15]
	s_setprio 0
	ds_read_b128 v[84:87], v234
	ds_read_b128 v[92:95], v238
	ds_read_b128 v[96:99], v238 offset:4096
	ds_read_b128 v[88:91], v234 offset:4096
	s_setprio 1
	s_waitcnt lgkmcnt(6)
	v_mfma_f32_32x32x16_bf16 v[48:63], v[102:105], v[110:113], v[48:63]
	s_waitcnt lgkmcnt(5)
	v_mfma_f32_32x32x16_bf16 v[32:47], v[102:105], v[114:117], v[32:47]
	s_waitcnt lgkmcnt(4)
	v_mfma_f32_32x32x16_bf16 v[16:31], v[106:109], v[110:113], v[16:31]
	v_mfma_f32_32x32x16_bf16 v[0:15], v[106:109], v[114:117], v[0:15]
	s_setprio 0
	ds_read_b128 v[102:105], v235
	ds_read_b128 v[110:113], v239
	ds_read_b128 v[114:117], v239 offset:4096
	ds_read_b128 v[106:109], v235 offset:4096
	s_setprio 1
	s_waitcnt lgkmcnt(6)
	v_mfma_f32_32x32x16_bf16 v[48:63], v[84:87], v[92:95], v[48:63]
	s_waitcnt lgkmcnt(5)
	v_mfma_f32_32x32x16_bf16 v[32:47], v[84:87], v[96:99], v[32:47]
	s_waitcnt lgkmcnt(4)
	v_mfma_f32_32x32x16_bf16 v[16:31], v[88:91], v[92:95], v[16:31]
	v_mfma_f32_32x32x16_bf16 v[0:15], v[88:91], v[96:99], v[0:15]
	s_setprio 0
	s_waitcnt lgkmcnt(0)
	s_waitcnt vmcnt(0)
	s_barrier
	ds_read_b128 v[84:87], v224
	ds_read_b128 v[92:95], v228
	ds_read_b128 v[96:99], v228 offset:4096
	ds_read_b128 v[88:91], v224 offset:4096
	s_setprio 1
	v_mfma_f32_32x32x16_bf16 v[48:63], v[102:105], v[110:113], v[48:63]
	v_mfma_f32_32x32x16_bf16 v[32:47], v[102:105], v[114:117], v[32:47]
	v_mfma_f32_32x32x16_bf16 v[16:31], v[106:109], v[110:113], v[16:31]
	v_mfma_f32_32x32x16_bf16 v[0:15], v[106:109], v[114:117], v[0:15]
	s_setprio 0
	ds_read_b128 v[102:105], v225
	ds_read_b128 v[110:113], v229
	ds_read_b128 v[114:117], v229 offset:4096
	ds_read_b128 v[106:109], v225 offset:4096
	s_setprio 1
	s_waitcnt lgkmcnt(6)
	v_mfma_f32_32x32x16_bf16 v[48:63], v[84:87], v[92:95], v[48:63]
	s_waitcnt lgkmcnt(5)
	v_mfma_f32_32x32x16_bf16 v[32:47], v[84:87], v[96:99], v[32:47]
	s_waitcnt lgkmcnt(4)
	v_mfma_f32_32x32x16_bf16 v[16:31], v[88:91], v[92:95], v[16:31]
	v_mfma_f32_32x32x16_bf16 v[0:15], v[88:91], v[96:99], v[0:15]
	s_setprio 0
	ds_read_b128 v[84:87], v226
	ds_read_b128 v[92:95], v230
	ds_read_b128 v[96:99], v230 offset:4096
	ds_read_b128 v[88:91], v226 offset:4096
	s_setprio 1
	s_waitcnt lgkmcnt(6)
	v_mfma_f32_32x32x16_bf16 v[48:63], v[102:105], v[110:113], v[48:63]
	s_waitcnt lgkmcnt(5)
	v_mfma_f32_32x32x16_bf16 v[32:47], v[102:105], v[114:117], v[32:47]
	s_waitcnt lgkmcnt(4)
	v_mfma_f32_32x32x16_bf16 v[16:31], v[106:109], v[110:113], v[16:31]
	v_mfma_f32_32x32x16_bf16 v[0:15], v[106:109], v[114:117], v[0:15]
	s_setprio 0
	ds_read_b128 v[102:105], v227
	ds_read_b128 v[110:113], v231
	ds_read_b128 v[114:117], v231 offset:4096
	ds_read_b128 v[106:109], v227 offset:4096
	s_setprio 1
	s_waitcnt lgkmcnt(6)
	v_mfma_f32_32x32x16_bf16 v[48:63], v[84:87], v[92:95], v[48:63]
	s_waitcnt lgkmcnt(5)
	v_mfma_f32_32x32x16_bf16 v[32:47], v[84:87], v[96:99], v[32:47]
	s_waitcnt lgkmcnt(4)
	v_mfma_f32_32x32x16_bf16 v[16:31], v[88:91], v[92:95], v[16:31]
	v_mfma_f32_32x32x16_bf16 v[0:15], v[88:91], v[96:99], v[0:15]
	s_setprio 0
	s_waitcnt lgkmcnt(0)
	s_waitcnt vmcnt(0)
	s_barrier
